# dwconv phase: LayerNorm gain/bias loaded once per phase instead of a per-row load ladder; wave sums via DPP + permlane32_swap
# speedup vs baseline: 1.0149x; 1.0149x over previous
; __global__ void __launch_bounds__(512, 2) fwd_kernel(Args a) {
;     ...
;         const int c2 = 2 * tid;
;         float wv[31][2];
; #pragma unroll
;         for (int j = 0; j < 31; ++j) { wv[j][0] = a.c_dww[j * DM + c2]; wv[j][1] = a.c_dww[j * DM + c2 + 1]; }
;         const float db0 = a.c_dwb[c2], db1 = a.c_dwb[c2 + 1];
;         const int TPB = (LSEQ + 15) / 16, NT_ = BATCH * TPB;
;         for (int tile = (int)blockIdx.x; tile < NT_; tile += G) {
.LBB0_1161:
	s_cmp_lt_i32 s78, 12
	s_cselect_b64 s[8:9], -1, 0
	s_and_b64 s[0:1], s[8:9], s[0:1]
	s_andn2_b64 vcc, exec, s[0:1]
	s_cbranch_vccnz .LBB0_1197
	s_cmpk_gt_i32 s2, 0x801
	s_cbranch_scc1 .LBB0_1197
	v_readlane_b32 s36, v247, 42
	v_readlane_b32 s40, v247, 46
	v_readlane_b32 s41, v247, 47
	v_lshlrev_b32_e32 v48, 3, v163
	v_mov_b32_e32 v49, 0
	v_readlane_b32 s42, v247, 48
	v_readlane_b32 s43, v247, 49
	v_readlane_b32 s44, v247, 50
	v_readlane_b32 s45, v247, 51
	v_readlane_b32 s46, v247, 52
	v_readlane_b32 s47, v247, 53
	s_mov_b64 s[20:21], s[40:41]
	s_waitcnt lgkmcnt(0)
	v_lshl_add_u64 v[0:1], s[20:21], 0, v[48:49]
	v_add_co_u32_e32 v2, vcc, 0x9000, v0
	s_mov_b64 s[22:23], s[42:43]
	s_nop 0
	v_addc_co_u32_e32 v3, vcc, 0, v1, vcc
	v_add_co_u32_e32 v4, vcc, 0xa000, v0
	v_readlane_b32 s37, v247, 43
	s_nop 0
	v_addc_co_u32_e32 v5, vcc, 0, v1, vcc
	v_add_co_u32_e32 v6, vcc, 0xb000, v0
	v_readlane_b32 s38, v247, 44
	s_nop 0
	v_addc_co_u32_e32 v7, vcc, 0, v1, vcc
	v_add_co_u32_e32 v8, vcc, 0xc000, v0
	v_readlane_b32 s39, v247, 45
	s_nop 0
	v_addc_co_u32_e32 v9, vcc, 0, v1, vcc
	global_load_dwordx2 v[50:51], v[2:3], off
	global_load_dwordx2 v[52:53], v[4:5], off
	global_load_dwordx2 v[54:55], v[6:7], off
	global_load_dwordx2 v[56:57], v[8:9], off
	v_add_co_u32_e32 v2, vcc, 0xd000, v0
	s_waitcnt vmcnt(0)
	v_or_b32_e32 v11, 0xc00, v163
	v_addc_co_u32_e32 v3, vcc, 0, v1, vcc
	v_add_co_u32_e32 v4, vcc, 0xe000, v0
	v_add_u32_e32 v12, 0xe00, v163
	s_nop 0
	v_addc_co_u32_e32 v5, vcc, 0, v1, vcc
	v_add_co_u32_e32 v6, vcc, 0xf000, v0
	v_or_b32_e32 v14, 0x1000, v163
	s_nop 0
	v_addc_co_u32_e32 v7, vcc, 0, v1, vcc
	v_add_co_u32_e32 v8, vcc, 0x10000, v0
	v_add_u32_e32 v15, 0x1200, v163
	s_nop 0
	v_addc_co_u32_e32 v9, vcc, 0, v1, vcc
	global_load_dwordx2 v[58:59], v[2:3], off
	global_load_dwordx2 v[60:61], v[4:5], off
	global_load_dwordx2 v[62:63], v[6:7], off
	global_load_dwordx2 v[64:65], v[8:9], off
	v_add_co_u32_e32 v2, vcc, 0x11000, v0
	v_or_b32_e32 v17, 0x1400, v163
	s_nop 0
	v_addc_co_u32_e32 v3, vcc, 0, v1, vcc
	v_add_co_u32_e32 v4, vcc, 0x12000, v0
	v_add_u32_e32 v18, 0x1600, v163
	s_nop 0
	v_addc_co_u32_e32 v5, vcc, 0, v1, vcc
	v_add_co_u32_e32 v6, vcc, 0x13000, v0
	s_mov_b64 s[24:25], s[44:45]
	s_nop 0
	v_addc_co_u32_e32 v7, vcc, 0, v1, vcc
	v_add_co_u32_e32 v8, vcc, 0x14000, v0
	s_mov_b64 s[26:27], s[46:47]
	s_nop 0
	v_addc_co_u32_e32 v9, vcc, 0, v1, vcc
	global_load_dwordx2 v[66:67], v[2:3], off
	global_load_dwordx2 v[68:69], v[4:5], off
	global_load_dwordx2 v[70:71], v[6:7], off
	global_load_dwordx2 v[72:73], v[8:9], off
	v_add_co_u32_e32 v2, vcc, 0x15000, v0
	v_lshlrev_b32_e32 v156, 2, v163
	s_nop 0
	v_addc_co_u32_e32 v3, vcc, 0, v1, vcc
	v_add_co_u32_e32 v4, vcc, 0x16000, v0
	v_lshlrev_b32_e32 v158, 1, v165
	s_nop 0
	v_addc_co_u32_e32 v5, vcc, 0, v1, vcc
	v_add_co_u32_e32 v6, vcc, 0x17000, v0
	v_readlane_b32 s36, v247, 0
	s_nop 0
	v_addc_co_u32_e32 v7, vcc, 0, v1, vcc
	v_add_co_u32_e32 v8, vcc, 0x18000, v0
	v_lshrrev_b32_e32 v13, 7, v12
	s_nop 0
	v_addc_co_u32_e32 v9, vcc, 0, v1, vcc
	global_load_dwordx2 v[74:75], v[2:3], off
	global_load_dwordx2 v[76:77], v[4:5], off
	global_load_dwordx2 v[78:79], v[6:7], off
	global_load_dwordx2 v[80:81], v[8:9], off
	v_add_co_u32_e32 v2, vcc, 0x19000, v0
	v_lshrrev_b32_e32 v16, 7, v15
	s_nop 0
	v_addc_co_u32_e32 v3, vcc, 0, v1, vcc
	v_add_co_u32_e32 v4, vcc, 0x1a000, v0
	s_movk_i32 s0, 0x1700
	s_nop 0
	v_addc_co_u32_e32 v5, vcc, 0, v1, vcc
	v_add_co_u32_e32 v6, vcc, 0x1b000, v0
	v_lshrrev_b32_e32 v19, 7, v18
	s_nop 0
	v_addc_co_u32_e32 v7, vcc, 0, v1, vcc
	v_add_co_u32_e32 v8, vcc, 0x1c000, v0
	v_lshlrev_b32_e32 v22, 4, v11
	s_nop 0
	v_addc_co_u32_e32 v9, vcc, 0, v1, vcc
	global_load_dwordx2 v[82:83], v[2:3], off
	global_load_dwordx2 v[84:85], v[4:5], off
	global_load_dwordx2 v[86:87], v[6:7], off
	global_load_dwordx2 v[88:89], v[8:9], off
	v_add_co_u32_e32 v2, vcc, 0x1d000, v0
	v_lshlrev_b32_e32 v12, 4, v12
	s_nop 0
	v_addc_co_u32_e32 v3, vcc, 0, v1, vcc
	v_add_co_u32_e32 v4, vcc, 0x1e000, v0
	v_lshlrev_b32_e32 v23, 4, v14
	s_nop 0
	v_addc_co_u32_e32 v5, vcc, 0, v1, vcc
	v_add_co_u32_e32 v6, vcc, 0x1000, v0
	v_lshlrev_b32_e32 v15, 4, v15
	s_nop 0
	v_addc_co_u32_e32 v7, vcc, 0, v1, vcc
	v_add_co_u32_e32 v8, vcc, 0x2000, v0
	v_lshlrev_b32_e32 v24, 4, v17
	s_nop 0
	v_addc_co_u32_e32 v9, vcc, 0, v1, vcc
	global_load_dwordx2 v[90:91], v[2:3], off
	global_load_dwordx2 v[92:93], v[4:5], off
	global_load_dwordx2 v[94:95], v[6:7], off
	global_load_dwordx2 v[96:97], v[8:9], off
	v_add_co_u32_e32 v2, vcc, 0x3000, v0
	v_lshlrev_b32_e32 v18, 4, v18
	s_nop 0
; #define LAS __attribute__((address_space(3)))
; __global__ void __launch_bounds__(512, 2) fwd_kernel(Args a) {
;     ...
;         const int c2 = 2 * tid;
;         float wv[31][2];
; #pragma unroll
;         for (int j = 0; j < 31; ++j) { wv[j][0] = a.c_dww[j * DM + c2]; wv[j][1] = a.c_dww[j * DM + c2 + 1]; }
;         const float db0 = a.c_dwb[c2], db1 = a.c_dwb[c2 + 1];
;         const int TPB = (LSEQ + 15) / 16, NT_ = BATCH * TPB;
;         for (int tile = (int)blockIdx.x; tile < NT_; tile += G) {
;             const int b = tile / TPB, t0 = (tile % TPB) * 16; const size_t rb = (size_t)b * LSEQ;
;             {
;                 u32x4 sv[12];
; #pragma unroll
;                 for (int k = 0; k < 12; ++k) { const int gi = tid + 512 * k, rr = gi >> 7, cc = gi & 127; const int t = t0 - 30 + rr;
;                     sv[k] = (u32x4){0u, 0u, 0u, 0u}; if (gi < 46 * 128 && t >= 0 && t < LSEQ) sv[k] = *(const u32x4*)(BIG + (rb + t) * DM + cc * 8); }
; #pragma unroll
;                 for (int k = 0; k < 12; ++k) { const int gi = tid + 512 * k, rr = gi >> 7, cc = gi & 127; if (gi < 46 * 128) *(LAS u32x4*)(lds + rr * 2048 + cc * 16) = sv[k]; }
;     ...
;                     for (int j = 0; j < 4; ++j) { const f32x4 gv = *((const f32x4*)a.c_lng + lane + 64 * j), bv = *((const f32x4*)a.c_lnb + lane + 64 * j);
	v_addc_co_u32_e32 v3, vcc, 0, v1, vcc
	v_add_co_u32_e32 v4, vcc, 0x4000, v0
	v_lshlrev_b32_e32 v165, 13, v165
	s_nop 0
	v_addc_co_u32_e32 v5, vcc, 0, v1, vcc
	v_add_co_u32_e32 v6, vcc, 0x5000, v0
	v_add_u32_e32 v157, 0, v156
	s_nop 0
	v_addc_co_u32_e32 v7, vcc, 0, v1, vcc
	v_add_co_u32_e32 v8, vcc, 0x6000, v0
	v_add_u32_e32 v159, 0, v166
	s_nop 0
	v_addc_co_u32_e32 v9, vcc, 0, v1, vcc
	global_load_dwordx2 v[98:99], v[2:3], off
	global_load_dwordx2 v[100:101], v[4:5], off
	global_load_dwordx2 v[102:103], v[6:7], off
	global_load_dwordx2 v[104:105], v[8:9], off
	v_add_co_u32_e32 v2, vcc, 0x7000, v0
	v_or_b32_e32 v5, 0x400, v163
	s_nop 0
	v_addc_co_u32_e32 v3, vcc, 0, v1, vcc
	v_add_co_u32_e32 v0, vcc, 0x8000, v0
	v_add_u32_e32 v6, 0x600, v163
	s_nop 0
	v_addc_co_u32_e32 v1, vcc, 0, v1, vcc
	global_load_dwordx2 v[106:107], v48, s[20:21]
	global_load_dwordx2 v[108:109], v[2:3], off
	global_load_dwordx2 v[110:111], v48, s[22:23]
	global_load_dwordx2 v[112:113], v[0:1], off
	v_lshlrev_b32_e32 v0, 4, v163
	v_add_u32_e32 v3, 0x200, v163
	v_or_b32_e32 v8, 0x800, v163
	v_add_u32_e32 v9, 0xa00, v163
	v_and_b32_e32 v48, 0x7f0, v0
	v_lshrrev_b32_e32 v4, 7, v3
	v_lshrrev_b32_e32 v7, 7, v6
	v_lshrrev_b32_e32 v10, 7, v9
	v_lshlrev_b32_e32 v3, 4, v3
	v_lshlrev_b32_e32 v20, 4, v5
	v_lshlrev_b32_e32 v6, 4, v6
	v_lshlrev_b32_e32 v21, 4, v8
	v_lshlrev_b32_e32 v9, 4, v9
	v_lshl_add_u64 v[114:115], s[18:19], 0, v[48:49]
	v_add_u32_e32 v1, 0, v48
	v_mov_b32_e32 v167, v49
	v_lshlrev_b32_e32 v48, 3, v164
	v_readlane_b32 s42, v247, 6
	v_readlane_b32 s43, v247, 7
	v_lshrrev_b32_e32 v2, 7, v163
	v_cmp_gt_u32_e64 s[4:5], s0, v17
	s_movk_i32 s0, 0x100
	v_and_b32_e32 v0, 0x3800, v0
	v_and_b32_e32 v3, 0x7800, v3
	v_and_b32_e32 v20, 0x7800, v20
	v_and_b32_e32 v6, 0xf800, v6
	v_and_b32_e32 v21, 0xb800, v21
	v_and_b32_e32 v9, 0xf800, v9
	v_and_b32_e32 v22, 0xf800, v22
	v_and_b32_e32 v12, 0x1f800, v12
	v_and_b32_e32 v23, 0x13800, v23
	v_and_b32_e32 v15, 0x17800, v15
	v_and_b32_e32 v24, 0x17800, v24
	v_and_b32_e32 v18, 0x16800, v18
	v_or_b32_e32 v25, 0x1000, v165
	v_lshrrev_b32_e32 v17, 7, v17
	v_lshrrev_b32_e32 v14, 7, v14
	v_lshrrev_b32_e32 v11, 7, v11
	v_lshrrev_b32_e32 v8, 7, v8
	v_lshrrev_b32_e32 v5, 7, v5
	v_lshl_add_u64 v[116:117], s[24:25], 0, v[166:167]
	v_lshl_add_u64 v[118:119], s[26:27], 0, v[166:167]
	global_load_dwordx4 v[212:215], v[116:117], off
	global_load_dwordx4 v[228:231], v[118:119], off
	global_load_dwordx4 v[216:219], v[116:117], off offset:1024
	global_load_dwordx4 v[232:235], v[118:119], off offset:1024
	global_load_dwordx4 v[220:223], v[116:117], off offset:2048
	global_load_dwordx4 v[236:239], v[118:119], off offset:2048
	global_load_dwordx4 v[224:227], v[116:117], off offset:3072
	global_load_dwordx4 v[240:243], v[118:119], off offset:3072
	v_lshl_add_u64 v[120:121], s[42:43], 0, v[48:49]
	v_cmp_gt_u32_e64 s[6:7], s0, v163
	v_add_u32_e32 v160, 0x10000, v157
	v_add_u32_e32 v161, 0x10800, v157
	v_add_u32_e32 v167, 0x11000, v157
	v_add_u32_e32 v168, 0x11800, v157
	v_add_u32_e32 v169, 0x12000, v157
	v_add_u32_e32 v170, 0x12800, v157
	v_add_u32_e32 v171, 0x13000, v157
	v_add_u32_e32 v172, 0x13800, v157
	v_add_u32_e32 v173, 0x14000, v157
	v_add_u32_e32 v174, 0x14800, v157
	v_add_u32_e32 v175, 0x15000, v157
	v_add_u32_e32 v176, 0x15800, v157
	v_add_u32_e32 v177, 0x16000, v157
	v_add_u32_e32 v178, 0x16800, v157
	s_lshl_b32 s3, s2, 4
	s_lshl_b32 s14, s88, 4
	v_subrev_u32_e32 v179, 30, v19
	v_subrev_u32_e32 v180, 30, v17
	v_subrev_u32_e32 v181, 30, v16
	v_subrev_u32_e32 v183, 30, v14
	v_subrev_u32_e32 v184, 30, v13
	v_subrev_u32_e32 v185, 30, v11
	v_subrev_u32_e32 v186, 30, v10
	v_subrev_u32_e32 v187, 30, v8
	v_subrev_u32_e32 v188, 30, v7
	v_subrev_u32_e32 v189, 30, v5
	v_subrev_u32_e32 v190, 30, v4
	v_subrev_u32_e32 v191, 30, v2
	s_movk_i32 s15, 0x4010
	v_add_u32_e32 v192, v1, v0
	v_add_u32_e32 v193, v1, v3
	v_add_u32_e32 v194, v1, v20
	v_add_u32_e32 v195, v1, v6
	v_add_u32_e32 v196, v1, v21
	v_add_u32_e32 v197, v1, v9
	v_add_u32_e32 v198, v1, v22
	v_add_u32_e32 v199, v1, v12
	v_add_u32_e32 v200, v1, v23
	v_add_u32_e32 v201, v1, v15
	v_add_u32_e32 v202, v1, v24
	v_add_u32_e32 v203, v1, v18
	v_mov_b32_e32 v204, 0x3727c5ac
	s_mov_b32 s16, 0xf800000
	v_mov_b32_e32 v205, 0x260
	v_add_u32_e32 v206, v159, v25
	s_mov_b32 s17, s2
	v_readlane_b32 s48, v247, 54
	v_readlane_b32 s49, v247, 55
	v_readlane_b32 s50, v247, 56
	v_readlane_b32 s51, v247, 57
	v_readlane_b32 s37, v247, 1
	v_readlane_b32 s38, v247, 2
	v_readlane_b32 s39, v247, 3
	v_readlane_b32 s40, v247, 4
	v_readlane_b32 s41, v247, 5
	s_branch .LBB0_1165

; #define LAS __attribute__((address_space(3)))
; __global__ void __launch_bounds__(512, 2) fwd_kernel(Args a) {
;     ...
;                 for (int k = 0; k < 12; ++k) { const int gi = tid + 512 * k, rr = gi >> 7, cc = gi & 127; const int t = t0 - 30 + rr;
;                     sv[k] = (u32x4){0u, 0u, 0u, 0u}; if (gi < 46 * 128 && t >= 0 && t < LSEQ) sv[k] = *(const u32x4*)(BIG + (rb + t) * DM + cc * 8); }
; #pragma unroll
;                 for (int k = 0; k < 12; ++k) { const int gi = tid + 512 * k, rr = gi >> 7, cc = gi & 127; if (gi < 46 * 128) *(LAS u32x4*)(lds + rr * 2048 + cc * 16) = sv[k]; }
;             }
;             __syncthreads();
;             float acc[16][2];
; #pragma unroll
;             for (int r = 0; r < 16; ++r) { acc[r][0] = db0; acc[r][1] = db1; }
; #pragma unroll
;             for (int j = 0; j < 31; ++j) {
; #pragma unroll
;                 for (int r = 0; r < 16; ++r) { const unsigned w = *(const LAS unsigned*)(lds + (r + j) * 2048 + tid * 4);
;                     acc[r][0] += wv[j][0] * bflo(w); acc[r][1] += wv[j][1] * bfhi(w); } }
.LBB0_1189:
	s_or_b64 exec, exec, s[0:1]
	s_waitcnt vmcnt(0)
	ds_write_b128 v192, v[0:3]
	ds_write_b128 v193, v[8:11]
	ds_write_b128 v194, v[4:7]
	ds_write_b128 v195, v[16:19]
	ds_write_b128 v196, v[12:15]
	ds_write_b128 v197, v[24:27]
	ds_write_b128 v198, v[20:23]
	ds_write_b128 v199, v[32:35]
	ds_write_b128 v200, v[28:31]
	ds_write_b128 v201, v[40:43]
	s_and_saveexec_b64 s[0:1], s[4:5]
	ds_write_b128 v202, v[36:39]
	s_or_b64 exec, exec, s[0:1]
	s_and_saveexec_b64 s[0:1], s[6:7]
	ds_write_b128 v203, v[44:47]
	s_or_b64 exec, exec, s[0:1]
	s_waitcnt lgkmcnt(0)
	s_barrier
	ds_read2st64_b32 v[0:1], v157 offset1:8
	ds_read2st64_b32 v[2:3], v157 offset0:16 offset1:24
	ds_read2st64_b32 v[36:37], v157 offset0:176 offset1:184
	s_waitcnt lgkmcnt(2)
	v_lshlrev_b32_e32 v6, 16, v0
	v_and_b32_e32 v7, 0xffff0000, v0
	v_lshlrev_b32_e32 v8, 16, v1
	v_and_b32_e32 v9, 0xffff0000, v1
	ds_read2st64_b32 v[0:1], v157 offset0:32 offset1:40
	s_waitcnt lgkmcnt(2)
	v_lshlrev_b32_e32 v10, 16, v2
	v_and_b32_e32 v11, 0xffff0000, v2
	v_lshlrev_b32_e32 v12, 16, v3
	v_and_b32_e32 v13, 0xffff0000, v3
	ds_read2st64_b32 v[2:3], v157 offset0:48 offset1:56
	v_pk_fma_f32 v[6:7], v[106:107], v[6:7], v[110:111]
	s_waitcnt lgkmcnt(1)
	v_lshlrev_b32_e32 v14, 16, v0
	v_pk_fma_f32 v[6:7], v[94:95], v[8:9], v[6:7]
	v_and_b32_e32 v15, 0xffff0000, v0
	v_lshlrev_b32_e32 v16, 16, v1
	v_and_b32_e32 v17, 0xffff0000, v1
	ds_read2st64_b32 v[0:1], v157 offset0:64 offset1:72
	v_pk_fma_f32 v[6:7], v[96:97], v[10:11], v[6:7]
	s_waitcnt lgkmcnt(1)
	v_lshlrev_b32_e32 v18, 16, v2
	v_pk_fma_f32 v[6:7], v[98:99], v[12:13], v[6:7]
	v_and_b32_e32 v19, 0xffff0000, v2
	v_pk_fma_f32 v[6:7], v[100:101], v[14:15], v[6:7]
	v_lshlrev_b32_e32 v20, 16, v3
	v_pk_fma_f32 v[6:7], v[102:103], v[16:17], v[6:7]
	v_and_b32_e32 v21, 0xffff0000, v3
	v_pk_fma_f32 v[6:7], v[104:105], v[18:19], v[6:7]
	s_waitcnt lgkmcnt(0)
	v_lshlrev_b32_e32 v22, 16, v0
	v_and_b32_e32 v23, 0xffff0000, v0
	v_pk_fma_f32 v[6:7], v[108:109], v[20:21], v[6:7]
	v_lshlrev_b32_e32 v122, 16, v1
	v_pk_fma_f32 v[124:125], v[112:113], v[22:23], v[6:7]
	v_pk_fma_f32 v[6:7], v[106:107], v[8:9], v[110:111]
	v_and_b32_e32 v123, 0xffff0000, v1
	v_pk_fma_f32 v[6:7], v[94:95], v[10:11], v[6:7]
	ds_read2st64_b32 v[2:3], v157 offset0:80 offset1:88
	v_pk_fma_f32 v[6:7], v[96:97], v[12:13], v[6:7]
	ds_read2st64_b32 v[0:1], v157 offset0:96 offset1:104
	v_pk_fma_f32 v[6:7], v[98:99], v[14:15], v[6:7]
	ds_read2st64_b32 v[8:9], v157 offset0:192 offset1:200
	v_pk_fma_f32 v[6:7], v[100:101], v[16:17], v[6:7]
	s_waitcnt lgkmcnt(2)
	v_lshlrev_b32_e32 v46, 16, v2
	v_pk_fma_f32 v[6:7], v[102:103], v[18:19], v[6:7]
	v_and_b32_e32 v47, 0xffff0000, v2
	v_pk_fma_f32 v[6:7], v[104:105], v[20:21], v[6:7]
	v_lshlrev_b32_e32 v44, 16, v3
	v_pk_fma_f32 v[6:7], v[108:109], v[22:23], v[6:7]
	v_and_b32_e32 v45, 0xffff0000, v3
	v_pk_fma_f32 v[126:127], v[112:113], v[122:123], v[6:7]
	v_pk_fma_f32 v[6:7], v[106:107], v[10:11], v[110:111]
	s_waitcnt lgkmcnt(1)
	v_lshlrev_b32_e32 v42, 16, v0
	v_pk_fma_f32 v[6:7], v[94:95], v[12:13], v[6:7]
	v_and_b32_e32 v43, 0xffff0000, v0
	v_pk_fma_f32 v[6:7], v[96:97], v[14:15], v[6:7]
	v_lshlrev_b32_e32 v38, 16, v1
	v_pk_fma_f32 v[6:7], v[98:99], v[16:17], v[6:7]
	v_and_b32_e32 v39, 0xffff0000, v1
	v_pk_fma_f32 v[6:7], v[100:101], v[18:19], v[6:7]
	ds_read2st64_b32 v[2:3], v157 offset0:112 offset1:120
	v_pk_fma_f32 v[6:7], v[102:103], v[20:21], v[6:7]
	ds_read2st64_b32 v[0:1], v157 offset0:128 offset1:136
	v_pk_fma_f32 v[6:7], v[104:105], v[22:23], v[6:7]
	s_waitcnt lgkmcnt(1)
	v_lshlrev_b32_e32 v34, 16, v2
	v_pk_fma_f32 v[6:7], v[108:109], v[122:123], v[6:7]
	v_and_b32_e32 v35, 0xffff0000, v2
	v_pk_fma_f32 v[128:129], v[112:113], v[46:47], v[6:7]
	v_pk_fma_f32 v[6:7], v[106:107], v[12:13], v[110:111]
	v_lshlrev_b32_e32 v32, 16, v3
	v_pk_fma_f32 v[6:7], v[94:95], v[14:15], v[6:7]
	v_and_b32_e32 v33, 0xffff0000, v3
	v_pk_fma_f32 v[6:7], v[96:97], v[16:17], v[6:7]
	s_waitcnt lgkmcnt(0)
	v_lshlrev_b32_e32 v30, 16, v0
	v_pk_fma_f32 v[6:7], v[98:99], v[18:19], v[6:7]
	v_and_b32_e32 v31, 0xffff0000, v0
	v_pk_fma_f32 v[6:7], v[100:101], v[20:21], v[6:7]
	v_lshlrev_b32_e32 v28, 16, v1
	v_pk_fma_f32 v[6:7], v[102:103], v[22:23], v[6:7]
	v_and_b32_e32 v29, 0xffff0000, v1
	v_pk_fma_f32 v[6:7], v[104:105], v[122:123], v[6:7]
	ds_read2st64_b32 v[2:3], v157 offset0:144 offset1:152
	v_pk_fma_f32 v[6:7], v[108:109], v[46:47], v[6:7]
	ds_read2st64_b32 v[0:1], v157 offset0:160 offset1:168
	v_pk_fma_f32 v[130:131], v[112:113], v[44:45], v[6:7]
	v_pk_fma_f32 v[6:7], v[106:107], v[14:15], v[110:111]
	s_waitcnt lgkmcnt(1)
	v_lshlrev_b32_e32 v26, 16, v2
	v_pk_fma_f32 v[6:7], v[94:95], v[16:17], v[6:7]
	v_and_b32_e32 v27, 0xffff0000, v2
	v_pk_fma_f32 v[6:7], v[96:97], v[18:19], v[6:7]
	v_lshlrev_b32_e32 v24, 16, v3
	v_pk_fma_f32 v[6:7], v[98:99], v[20:21], v[6:7]
	v_and_b32_e32 v25, 0xffff0000, v3
	v_pk_fma_f32 v[6:7], v[100:101], v[22:23], v[6:7]
	s_waitcnt lgkmcnt(0)
; #define LAS __attribute__((address_space(3)))
; __global__ void __launch_bounds__(512, 2) fwd_kernel(Args a) {
;     ...
;             for (int j = 0; j < 31; ++j) {
; #pragma unroll
;                 for (int r = 0; r < 16; ++r) { const unsigned w = *(const LAS unsigned*)(lds + (r + j) * 2048 + tid * 4);
;                     acc[r][0] += wv[j][0] * bflo(w); acc[r][1] += wv[j][1] * bfhi(w); } }
	v_lshlrev_b32_e32 v4, 16, v0
	v_pk_fma_f32 v[6:7], v[102:103], v[122:123], v[6:7]
	v_and_b32_e32 v5, 0xffff0000, v0
	v_pk_fma_f32 v[6:7], v[104:105], v[46:47], v[6:7]
	v_lshlrev_b32_e32 v2, 16, v1
	v_pk_fma_f32 v[6:7], v[108:109], v[44:45], v[6:7]
	v_and_b32_e32 v3, 0xffff0000, v1
	v_pk_fma_f32 v[132:133], v[112:113], v[42:43], v[6:7]
	v_pk_fma_f32 v[6:7], v[106:107], v[16:17], v[110:111]
	v_lshlrev_b32_e32 v0, 16, v36
	v_pk_fma_f32 v[6:7], v[94:95], v[18:19], v[6:7]
	v_and_b32_e32 v1, 0xffff0000, v36
	v_pk_fma_f32 v[6:7], v[96:97], v[20:21], v[6:7]
	s_nop 0
	v_pk_fma_f32 v[6:7], v[98:99], v[22:23], v[6:7]
	s_nop 0
	v_pk_fma_f32 v[6:7], v[100:101], v[122:123], v[6:7]
	s_nop 0
	v_pk_fma_f32 v[6:7], v[102:103], v[46:47], v[6:7]
	s_nop 0
	v_pk_fma_f32 v[6:7], v[104:105], v[44:45], v[6:7]
	s_nop 0
	v_pk_fma_f32 v[6:7], v[108:109], v[42:43], v[6:7]
	s_nop 0
	v_pk_fma_f32 v[134:135], v[112:113], v[38:39], v[6:7]
	v_pk_fma_f32 v[6:7], v[106:107], v[18:19], v[110:111]
	v_lshlrev_b32_e32 v18, 16, v37
	v_pk_fma_f32 v[6:7], v[94:95], v[20:21], v[6:7]
	v_and_b32_e32 v19, 0xffff0000, v37
	v_pk_fma_f32 v[6:7], v[96:97], v[22:23], v[6:7]
	s_nop 0
	v_pk_fma_f32 v[6:7], v[98:99], v[122:123], v[6:7]
	s_nop 0
	v_pk_fma_f32 v[6:7], v[100:101], v[46:47], v[6:7]
	s_nop 0
	v_pk_fma_f32 v[6:7], v[102:103], v[44:45], v[6:7]
	s_nop 0
	v_pk_fma_f32 v[6:7], v[104:105], v[42:43], v[6:7]
	s_nop 0
	v_pk_fma_f32 v[6:7], v[108:109], v[38:39], v[6:7]
	s_nop 0
	v_pk_fma_f32 v[136:137], v[112:113], v[34:35], v[6:7]
	v_pk_fma_f32 v[6:7], v[106:107], v[20:21], v[110:111]
	v_lshlrev_b32_e32 v20, 16, v9
	v_pk_fma_f32 v[6:7], v[94:95], v[22:23], v[6:7]
	v_and_b32_e32 v21, 0xffff0000, v9
	v_pk_fma_f32 v[6:7], v[96:97], v[122:123], v[6:7]
	s_nop 0
	v_pk_fma_f32 v[6:7], v[98:99], v[46:47], v[6:7]
	s_nop 0
	v_pk_fma_f32 v[6:7], v[100:101], v[44:45], v[6:7]
	s_nop 0
	v_pk_fma_f32 v[6:7], v[102:103], v[42:43], v[6:7]
	s_nop 0
	v_pk_fma_f32 v[6:7], v[104:105], v[38:39], v[6:7]
	s_nop 0
	v_pk_fma_f32 v[6:7], v[108:109], v[34:35], v[6:7]
	s_nop 0
	v_pk_fma_f32 v[138:139], v[112:113], v[32:33], v[6:7]
	v_pk_fma_f32 v[6:7], v[106:107], v[22:23], v[110:111]
	v_lshlrev_b32_e32 v22, 16, v8
	v_pk_fma_f32 v[6:7], v[94:95], v[122:123], v[6:7]
	v_and_b32_e32 v23, 0xffff0000, v8
	v_pk_fma_f32 v[6:7], v[96:97], v[46:47], v[6:7]
	ds_read2st64_b32 v[8:9], v157 offset0:224 offset1:232
	v_pk_fma_f32 v[6:7], v[98:99], v[44:45], v[6:7]
	s_waitcnt lgkmcnt(0)
	v_lshlrev_b32_e32 v12, 16, v8
	v_pk_fma_f32 v[6:7], v[100:101], v[42:43], v[6:7]
	v_and_b32_e32 v13, 0xffff0000, v8
	v_pk_fma_f32 v[6:7], v[102:103], v[38:39], v[6:7]
	v_lshlrev_b32_e32 v10, 16, v9
	v_pk_fma_f32 v[6:7], v[104:105], v[34:35], v[6:7]
	v_and_b32_e32 v11, 0xffff0000, v9
	v_pk_fma_f32 v[6:7], v[108:109], v[32:33], v[6:7]
	s_nop 0
	v_pk_fma_f32 v[140:141], v[112:113], v[30:31], v[6:7]
	v_pk_fma_f32 v[6:7], v[106:107], v[122:123], v[110:111]
	v_pk_fma_f32 v[122:123], v[50:51], v[122:123], v[124:125]
	v_pk_fma_f32 v[6:7], v[94:95], v[46:47], v[6:7]
	v_pk_fma_f32 v[122:123], v[52:53], v[46:47], v[122:123]
	v_pk_fma_f32 v[6:7], v[96:97], v[44:45], v[6:7]
	v_pk_fma_f32 v[122:123], v[54:55], v[44:45], v[122:123]
	v_pk_fma_f32 v[6:7], v[98:99], v[42:43], v[6:7]
	v_pk_fma_f32 v[122:123], v[56:57], v[42:43], v[122:123]
	v_pk_fma_f32 v[6:7], v[100:101], v[38:39], v[6:7]
	v_pk_fma_f32 v[122:123], v[58:59], v[38:39], v[122:123]
	v_pk_fma_f32 v[6:7], v[102:103], v[34:35], v[6:7]
	v_pk_fma_f32 v[122:123], v[60:61], v[34:35], v[122:123]
	v_pk_fma_f32 v[6:7], v[104:105], v[32:33], v[6:7]
	v_pk_fma_f32 v[122:123], v[62:63], v[32:33], v[122:123]
	v_pk_fma_f32 v[6:7], v[108:109], v[30:31], v[6:7]
	v_pk_fma_f32 v[122:123], v[64:65], v[30:31], v[122:123]
	v_pk_fma_f32 v[142:143], v[112:113], v[28:29], v[6:7]
	v_pk_fma_f32 v[6:7], v[106:107], v[46:47], v[110:111]
	v_pk_fma_f32 v[46:47], v[50:51], v[46:47], v[126:127]
	v_pk_fma_f32 v[6:7], v[94:95], v[44:45], v[6:7]
	v_pk_fma_f32 v[46:47], v[52:53], v[44:45], v[46:47]
	v_pk_fma_f32 v[6:7], v[96:97], v[42:43], v[6:7]
	v_pk_fma_f32 v[46:47], v[54:55], v[42:43], v[46:47]
	v_pk_fma_f32 v[6:7], v[98:99], v[38:39], v[6:7]
	v_pk_fma_f32 v[46:47], v[56:57], v[38:39], v[46:47]
	v_pk_fma_f32 v[6:7], v[100:101], v[34:35], v[6:7]
	v_pk_fma_f32 v[46:47], v[58:59], v[34:35], v[46:47]
	v_pk_fma_f32 v[6:7], v[102:103], v[32:33], v[6:7]
	v_pk_fma_f32 v[46:47], v[60:61], v[32:33], v[46:47]
	v_pk_fma_f32 v[6:7], v[104:105], v[30:31], v[6:7]
	v_pk_fma_f32 v[46:47], v[62:63], v[30:31], v[46:47]
	v_pk_fma_f32 v[6:7], v[108:109], v[28:29], v[6:7]
	v_pk_fma_f32 v[122:123], v[66:67], v[28:29], v[122:123]
	v_pk_fma_f32 v[144:145], v[112:113], v[26:27], v[6:7]
	v_pk_fma_f32 v[6:7], v[106:107], v[44:45], v[110:111]
	v_pk_fma_f32 v[44:45], v[50:51], v[44:45], v[128:129]
	v_pk_fma_f32 v[6:7], v[94:95], v[42:43], v[6:7]
	v_pk_fma_f32 v[44:45], v[52:53], v[42:43], v[44:45]
	v_pk_fma_f32 v[6:7], v[96:97], v[38:39], v[6:7]
	v_pk_fma_f32 v[44:45], v[54:55], v[38:39], v[44:45]
	v_pk_fma_f32 v[6:7], v[98:99], v[34:35], v[6:7]
	v_pk_fma_f32 v[44:45], v[56:57], v[34:35], v[44:45]
	v_pk_fma_f32 v[6:7], v[100:101], v[32:33], v[6:7]
	v_pk_fma_f32 v[44:45], v[58:59], v[32:33], v[44:45]
	v_pk_fma_f32 v[6:7], v[102:103], v[30:31], v[6:7]
	v_pk_fma_f32 v[44:45], v[60:61], v[30:31], v[44:45]
	v_pk_fma_f32 v[6:7], v[104:105], v[28:29], v[6:7]
	v_pk_fma_f32 v[46:47], v[64:65], v[28:29], v[46:47]
	v_pk_fma_f32 v[6:7], v[108:109], v[26:27], v[6:7]
	v_pk_fma_f32 v[44:45], v[62:63], v[28:29], v[44:45]
	v_pk_fma_f32 v[146:147], v[112:113], v[24:25], v[6:7]
	v_pk_fma_f32 v[6:7], v[106:107], v[42:43], v[110:111]
	v_pk_fma_f32 v[42:43], v[50:51], v[42:43], v[130:131]
; #define LAS __attribute__((address_space(3)))
; __global__ void __launch_bounds__(512, 2) fwd_kernel(Args a) {
;     ...
;             for (int j = 0; j < 31; ++j) {
; #pragma unroll
;                 for (int r = 0; r < 16; ++r) { const unsigned w = *(const LAS unsigned*)(lds + (r + j) * 2048 + tid * 4);
;                     acc[r][0] += wv[j][0] * bflo(w); acc[r][1] += wv[j][1] * bfhi(w); } }
	v_pk_fma_f32 v[6:7], v[94:95], v[38:39], v[6:7]
	v_pk_fma_f32 v[42:43], v[52:53], v[38:39], v[42:43]
	v_pk_fma_f32 v[6:7], v[96:97], v[34:35], v[6:7]
	v_pk_fma_f32 v[42:43], v[54:55], v[34:35], v[42:43]
	v_pk_fma_f32 v[6:7], v[98:99], v[32:33], v[6:7]
	v_pk_fma_f32 v[42:43], v[56:57], v[32:33], v[42:43]
	v_pk_fma_f32 v[6:7], v[100:101], v[30:31], v[6:7]
	v_pk_fma_f32 v[42:43], v[58:59], v[30:31], v[42:43]
	v_pk_fma_f32 v[6:7], v[102:103], v[28:29], v[6:7]
	v_pk_fma_f32 v[42:43], v[60:61], v[28:29], v[42:43]
	v_pk_fma_f32 v[6:7], v[104:105], v[26:27], v[6:7]
	v_pk_fma_f32 v[122:123], v[68:69], v[26:27], v[122:123]
	v_pk_fma_f32 v[6:7], v[108:109], v[24:25], v[6:7]
	v_pk_fma_f32 v[46:47], v[66:67], v[26:27], v[46:47]
	v_pk_fma_f32 v[148:149], v[112:113], v[4:5], v[6:7]
	v_pk_fma_f32 v[6:7], v[106:107], v[38:39], v[110:111]
	v_pk_fma_f32 v[38:39], v[50:51], v[38:39], v[132:133]
	v_pk_fma_f32 v[6:7], v[94:95], v[34:35], v[6:7]
	v_pk_fma_f32 v[38:39], v[52:53], v[34:35], v[38:39]
	v_pk_fma_f32 v[6:7], v[96:97], v[32:33], v[6:7]
	v_pk_fma_f32 v[38:39], v[54:55], v[32:33], v[38:39]
	v_pk_fma_f32 v[6:7], v[98:99], v[30:31], v[6:7]
	v_pk_fma_f32 v[38:39], v[56:57], v[30:31], v[38:39]
	v_pk_fma_f32 v[6:7], v[100:101], v[28:29], v[6:7]
	v_pk_fma_f32 v[38:39], v[58:59], v[28:29], v[38:39]
	v_pk_fma_f32 v[6:7], v[102:103], v[26:27], v[6:7]
	v_pk_fma_f32 v[44:45], v[64:65], v[26:27], v[44:45]
	v_pk_fma_f32 v[6:7], v[104:105], v[24:25], v[6:7]
	v_pk_fma_f32 v[42:43], v[62:63], v[26:27], v[42:43]
	v_pk_fma_f32 v[6:7], v[108:109], v[4:5], v[6:7]
	v_pk_fma_f32 v[38:39], v[60:61], v[26:27], v[38:39]
	v_pk_fma_f32 v[150:151], v[112:113], v[2:3], v[6:7]
	v_pk_fma_f32 v[6:7], v[106:107], v[34:35], v[110:111]
	v_pk_fma_f32 v[34:35], v[50:51], v[34:35], v[134:135]
	v_pk_fma_f32 v[6:7], v[94:95], v[32:33], v[6:7]
	v_pk_fma_f32 v[34:35], v[52:53], v[32:33], v[34:35]
	v_pk_fma_f32 v[6:7], v[96:97], v[30:31], v[6:7]
	v_pk_fma_f32 v[34:35], v[54:55], v[30:31], v[34:35]
	v_pk_fma_f32 v[6:7], v[98:99], v[28:29], v[6:7]
	v_pk_fma_f32 v[34:35], v[56:57], v[28:29], v[34:35]
	v_pk_fma_f32 v[6:7], v[100:101], v[26:27], v[6:7]
	v_pk_fma_f32 v[34:35], v[58:59], v[26:27], v[34:35]
	v_pk_fma_f32 v[6:7], v[102:103], v[24:25], v[6:7]
	v_pk_fma_f32 v[122:123], v[70:71], v[24:25], v[122:123]
	v_pk_fma_f32 v[6:7], v[104:105], v[4:5], v[6:7]
	v_pk_fma_f32 v[46:47], v[68:69], v[24:25], v[46:47]
	v_pk_fma_f32 v[6:7], v[108:109], v[2:3], v[6:7]
	v_pk_fma_f32 v[44:45], v[66:67], v[24:25], v[44:45]
	v_pk_fma_f32 v[152:153], v[112:113], v[0:1], v[6:7]
	v_pk_fma_f32 v[6:7], v[106:107], v[32:33], v[110:111]
	v_pk_fma_f32 v[32:33], v[50:51], v[32:33], v[136:137]
	v_pk_fma_f32 v[6:7], v[94:95], v[30:31], v[6:7]
	v_pk_fma_f32 v[32:33], v[52:53], v[30:31], v[32:33]
	v_pk_fma_f32 v[6:7], v[96:97], v[28:29], v[6:7]
	v_pk_fma_f32 v[30:31], v[50:51], v[30:31], v[138:139]
	v_pk_fma_f32 v[6:7], v[98:99], v[26:27], v[6:7]
	v_pk_fma_f32 v[32:33], v[54:55], v[28:29], v[32:33]
	v_pk_fma_f32 v[6:7], v[100:101], v[24:25], v[6:7]
	v_pk_fma_f32 v[30:31], v[52:53], v[28:29], v[30:31]
	v_pk_fma_f32 v[6:7], v[102:103], v[4:5], v[6:7]
	v_pk_fma_f32 v[28:29], v[50:51], v[28:29], v[140:141]
	v_pk_fma_f32 v[6:7], v[104:105], v[2:3], v[6:7]
	v_pk_fma_f32 v[32:33], v[56:57], v[26:27], v[32:33]
	v_pk_fma_f32 v[6:7], v[108:109], v[0:1], v[6:7]
	v_pk_fma_f32 v[30:31], v[54:55], v[26:27], v[30:31]
	v_pk_fma_f32 v[154:155], v[112:113], v[18:19], v[6:7]
	ds_read2st64_b32 v[6:7], v157 offset0:208 offset1:216
	v_pk_fma_f32 v[28:29], v[52:53], v[26:27], v[28:29]
	v_pk_fma_f32 v[26:27], v[50:51], v[26:27], v[142:143]
	v_pk_fma_f32 v[42:43], v[64:65], v[24:25], v[42:43]
	v_pk_fma_f32 v[38:39], v[62:63], v[24:25], v[38:39]
	s_waitcnt lgkmcnt(0)
	v_lshlrev_b32_e32 v16, 16, v6
	v_and_b32_e32 v17, 0xffff0000, v6
	v_lshlrev_b32_e32 v14, 16, v7
	v_and_b32_e32 v15, 0xffff0000, v7
	ds_read2st64_b32 v[6:7], v157 offset0:240 offset1:248
	v_pk_fma_f32 v[34:35], v[60:61], v[24:25], v[34:35]
	v_pk_fma_f32 v[32:33], v[58:59], v[24:25], v[32:33]
	v_pk_fma_f32 v[30:31], v[56:57], v[24:25], v[30:31]
	v_pk_fma_f32 v[28:29], v[54:55], v[24:25], v[28:29]
	v_pk_fma_f32 v[26:27], v[52:53], v[24:25], v[26:27]
	v_pk_fma_f32 v[24:25], v[50:51], v[24:25], v[144:145]
	v_pk_fma_f32 v[132:133], v[50:51], v[22:23], v[154:155]
	v_pk_fma_f32 v[46:47], v[70:71], v[4:5], v[46:47]
	v_pk_fma_f32 v[44:45], v[68:69], v[4:5], v[44:45]
	v_pk_fma_f32 v[42:43], v[66:67], v[4:5], v[42:43]
	v_pk_fma_f32 v[38:39], v[64:65], v[4:5], v[38:39]
	v_pk_fma_f32 v[34:35], v[62:63], v[4:5], v[34:35]
	v_pk_fma_f32 v[32:33], v[60:61], v[4:5], v[32:33]
	v_pk_fma_f32 v[30:31], v[58:59], v[4:5], v[30:31]
	v_pk_fma_f32 v[28:29], v[56:57], v[4:5], v[28:29]
	v_pk_fma_f32 v[26:27], v[54:55], v[4:5], v[26:27]
	v_pk_fma_f32 v[24:25], v[52:53], v[4:5], v[24:25]
	v_pk_fma_f32 v[124:125], v[50:51], v[4:5], v[146:147]
	v_pk_fma_f32 v[126:127], v[50:51], v[2:3], v[148:149]
	v_pk_fma_f32 v[128:129], v[50:51], v[0:1], v[150:151]
	v_pk_fma_f32 v[130:131], v[50:51], v[18:19], v[152:153]
	v_pk_fma_f32 v[132:133], v[52:53], v[20:21], v[132:133]
	v_pk_fma_f32 v[4:5], v[72:73], v[4:5], v[122:123]
	v_pk_fma_f32 v[44:45], v[70:71], v[2:3], v[44:45]
	v_pk_fma_f32 v[42:43], v[68:69], v[2:3], v[42:43]
	v_pk_fma_f32 v[38:39], v[66:67], v[2:3], v[38:39]
	v_pk_fma_f32 v[34:35], v[64:65], v[2:3], v[34:35]
	v_pk_fma_f32 v[32:33], v[62:63], v[2:3], v[32:33]
	v_pk_fma_f32 v[30:31], v[60:61], v[2:3], v[30:31]
	v_pk_fma_f32 v[28:29], v[58:59], v[2:3], v[28:29]
	v_pk_fma_f32 v[26:27], v[56:57], v[2:3], v[26:27]
	v_pk_fma_f32 v[24:25], v[54:55], v[2:3], v[24:25]
	v_pk_fma_f32 v[124:125], v[52:53], v[2:3], v[124:125]
; #define LAS __attribute__((address_space(3)))
; __global__ void __launch_bounds__(512, 2) fwd_kernel(Args a) {
;     ...
;             for (int j = 0; j < 31; ++j) {
; #pragma unroll
;                 for (int r = 0; r < 16; ++r) { const unsigned w = *(const LAS unsigned*)(lds + (r + j) * 2048 + tid * 4);
;                     acc[r][0] += wv[j][0] * bflo(w); acc[r][1] += wv[j][1] * bfhi(w); } }
	v_pk_fma_f32 v[126:127], v[52:53], v[0:1], v[126:127]
	v_pk_fma_f32 v[128:129], v[52:53], v[18:19], v[128:129]
	v_pk_fma_f32 v[130:131], v[52:53], v[22:23], v[130:131]
	v_pk_fma_f32 v[132:133], v[54:55], v[16:17], v[132:133]
	v_pk_fma_f32 v[4:5], v[74:75], v[2:3], v[4:5]
	v_pk_fma_f32 v[2:3], v[72:73], v[2:3], v[46:47]
	v_pk_fma_f32 v[42:43], v[70:71], v[0:1], v[42:43]
	v_pk_fma_f32 v[38:39], v[68:69], v[0:1], v[38:39]
	v_pk_fma_f32 v[34:35], v[66:67], v[0:1], v[34:35]
	v_pk_fma_f32 v[32:33], v[64:65], v[0:1], v[32:33]
	v_pk_fma_f32 v[30:31], v[62:63], v[0:1], v[30:31]
	v_pk_fma_f32 v[28:29], v[60:61], v[0:1], v[28:29]
	v_pk_fma_f32 v[26:27], v[58:59], v[0:1], v[26:27]
	v_pk_fma_f32 v[24:25], v[56:57], v[0:1], v[24:25]
	v_pk_fma_f32 v[124:125], v[54:55], v[0:1], v[124:125]
	v_pk_fma_f32 v[126:127], v[54:55], v[18:19], v[126:127]
	v_pk_fma_f32 v[128:129], v[54:55], v[22:23], v[128:129]
	v_pk_fma_f32 v[130:131], v[54:55], v[20:21], v[130:131]
	v_pk_fma_f32 v[132:133], v[56:57], v[14:15], v[132:133]
	v_pk_fma_f32 v[4:5], v[76:77], v[0:1], v[4:5]
	v_pk_fma_f32 v[2:3], v[74:75], v[0:1], v[2:3]
	v_pk_fma_f32 v[0:1], v[72:73], v[0:1], v[44:45]
	v_pk_fma_f32 v[38:39], v[70:71], v[18:19], v[38:39]
	v_pk_fma_f32 v[34:35], v[68:69], v[18:19], v[34:35]
	v_pk_fma_f32 v[32:33], v[66:67], v[18:19], v[32:33]
	v_pk_fma_f32 v[30:31], v[64:65], v[18:19], v[30:31]
	v_pk_fma_f32 v[28:29], v[62:63], v[18:19], v[28:29]
	v_pk_fma_f32 v[26:27], v[60:61], v[18:19], v[26:27]
	v_pk_fma_f32 v[24:25], v[58:59], v[18:19], v[24:25]
	v_pk_fma_f32 v[124:125], v[56:57], v[18:19], v[124:125]
	v_pk_fma_f32 v[126:127], v[56:57], v[22:23], v[126:127]
	v_pk_fma_f32 v[128:129], v[56:57], v[20:21], v[128:129]
	v_pk_fma_f32 v[130:131], v[56:57], v[16:17], v[130:131]
	v_pk_fma_f32 v[132:133], v[58:59], v[12:13], v[132:133]
	v_pk_fma_f32 v[4:5], v[78:79], v[18:19], v[4:5]
	v_pk_fma_f32 v[2:3], v[76:77], v[18:19], v[2:3]
	v_pk_fma_f32 v[0:1], v[74:75], v[18:19], v[0:1]
	v_pk_fma_f32 v[18:19], v[72:73], v[18:19], v[42:43]
	s_waitcnt lgkmcnt(0)
	v_lshlrev_b32_e32 v8, 16, v6
	v_and_b32_e32 v9, 0xffff0000, v6
	v_pk_fma_f32 v[34:35], v[70:71], v[22:23], v[34:35]
	v_pk_fma_f32 v[32:33], v[68:69], v[22:23], v[32:33]
	v_pk_fma_f32 v[30:31], v[66:67], v[22:23], v[30:31]
	v_pk_fma_f32 v[28:29], v[64:65], v[22:23], v[28:29]
	v_pk_fma_f32 v[26:27], v[62:63], v[22:23], v[26:27]
	v_pk_fma_f32 v[24:25], v[60:61], v[22:23], v[24:25]
	v_pk_fma_f32 v[124:125], v[58:59], v[22:23], v[124:125]
	v_pk_fma_f32 v[126:127], v[58:59], v[20:21], v[126:127]
	v_pk_fma_f32 v[128:129], v[58:59], v[16:17], v[128:129]
	v_pk_fma_f32 v[130:131], v[58:59], v[14:15], v[130:131]
	v_pk_fma_f32 v[132:133], v[60:61], v[10:11], v[132:133]
	v_pk_fma_f32 v[4:5], v[80:81], v[22:23], v[4:5]
	v_pk_fma_f32 v[2:3], v[78:79], v[22:23], v[2:3]
	v_pk_fma_f32 v[0:1], v[76:77], v[22:23], v[0:1]
	v_pk_fma_f32 v[18:19], v[74:75], v[22:23], v[18:19]
	v_pk_fma_f32 v[22:23], v[72:73], v[22:23], v[38:39]
	v_lshlrev_b32_e32 v6, 16, v7
	v_and_b32_e32 v7, 0xffff0000, v7
	v_pk_fma_f32 v[32:33], v[70:71], v[20:21], v[32:33]
	v_pk_fma_f32 v[30:31], v[68:69], v[20:21], v[30:31]
	v_pk_fma_f32 v[28:29], v[66:67], v[20:21], v[28:29]
	v_pk_fma_f32 v[26:27], v[64:65], v[20:21], v[26:27]
	v_pk_fma_f32 v[24:25], v[62:63], v[20:21], v[24:25]
	v_pk_fma_f32 v[124:125], v[60:61], v[20:21], v[124:125]
	v_pk_fma_f32 v[126:127], v[60:61], v[16:17], v[126:127]
	v_pk_fma_f32 v[128:129], v[60:61], v[14:15], v[128:129]
	v_pk_fma_f32 v[130:131], v[60:61], v[12:13], v[130:131]
	v_pk_fma_f32 v[132:133], v[62:63], v[8:9], v[132:133]
	v_pk_fma_f32 v[4:5], v[82:83], v[20:21], v[4:5]
	v_pk_fma_f32 v[2:3], v[80:81], v[20:21], v[2:3]
	v_pk_fma_f32 v[0:1], v[78:79], v[20:21], v[0:1]
	v_pk_fma_f32 v[18:19], v[76:77], v[20:21], v[18:19]
	v_pk_fma_f32 v[22:23], v[74:75], v[20:21], v[22:23]
	v_pk_fma_f32 v[20:21], v[72:73], v[20:21], v[34:35]
	ds_read_b32 v36, v160
	ds_read_b32 v37, v161
	ds_read_b32 v48, v167
	ds_read_b32 v207, v168
	ds_read_b32 v208, v169
	ds_read_b32 v209, v170
	ds_read_b32 v210, v171
	ds_read_b32 v211, v172
	s_waitcnt lgkmcnt(7)
	v_lshlrev_b32_e32 v40, 16, v36
	v_and_b32_e32 v41, 0xffff0000, v36
	v_pk_fma_f32 v[30:31], v[70:71], v[16:17], v[30:31]
	v_pk_fma_f32 v[28:29], v[68:69], v[16:17], v[28:29]
	v_pk_fma_f32 v[26:27], v[66:67], v[16:17], v[26:27]
	v_pk_fma_f32 v[24:25], v[64:65], v[16:17], v[24:25]
	v_pk_fma_f32 v[124:125], v[62:63], v[16:17], v[124:125]
	v_pk_fma_f32 v[126:127], v[62:63], v[14:15], v[126:127]
	v_pk_fma_f32 v[128:129], v[62:63], v[12:13], v[128:129]
	v_pk_fma_f32 v[130:131], v[62:63], v[10:11], v[130:131]
	v_pk_fma_f32 v[132:133], v[64:65], v[6:7], v[132:133]
	v_pk_fma_f32 v[4:5], v[84:85], v[16:17], v[4:5]
	v_pk_fma_f32 v[2:3], v[82:83], v[16:17], v[2:3]
	v_pk_fma_f32 v[0:1], v[80:81], v[16:17], v[0:1]
	v_pk_fma_f32 v[18:19], v[78:79], v[16:17], v[18:19]
	v_pk_fma_f32 v[22:23], v[76:77], v[16:17], v[22:23]
	v_pk_fma_f32 v[20:21], v[74:75], v[16:17], v[20:21]
	v_pk_fma_f32 v[16:17], v[72:73], v[16:17], v[32:33]
	s_waitcnt lgkmcnt(6)
; #define LAS __attribute__((address_space(3)))
; __global__ void __launch_bounds__(512, 2) fwd_kernel(Args a) {
;     ...
;             for (int j = 0; j < 31; ++j) {
; #pragma unroll
;                 for (int r = 0; r < 16; ++r) { const unsigned w = *(const LAS unsigned*)(lds + (r + j) * 2048 + tid * 4);
;                     acc[r][0] += wv[j][0] * bflo(w); acc[r][1] += wv[j][1] * bfhi(w); } }
	v_lshlrev_b32_e32 v36, 16, v37
	v_and_b32_e32 v37, 0xffff0000, v37
	v_pk_fma_f32 v[28:29], v[70:71], v[14:15], v[28:29]
	v_pk_fma_f32 v[26:27], v[68:69], v[14:15], v[26:27]
	v_pk_fma_f32 v[24:25], v[66:67], v[14:15], v[24:25]
	v_pk_fma_f32 v[124:125], v[64:65], v[14:15], v[124:125]
	v_pk_fma_f32 v[126:127], v[64:65], v[12:13], v[126:127]
	v_pk_fma_f32 v[128:129], v[64:65], v[10:11], v[128:129]
	v_pk_fma_f32 v[130:131], v[64:65], v[8:9], v[130:131]
	v_pk_fma_f32 v[132:133], v[66:67], v[40:41], v[132:133]
	v_pk_fma_f32 v[4:5], v[86:87], v[14:15], v[4:5]
	v_pk_fma_f32 v[2:3], v[84:85], v[14:15], v[2:3]
	v_pk_fma_f32 v[0:1], v[82:83], v[14:15], v[0:1]
	v_pk_fma_f32 v[18:19], v[80:81], v[14:15], v[18:19]
	v_pk_fma_f32 v[22:23], v[78:79], v[14:15], v[22:23]
	v_pk_fma_f32 v[20:21], v[76:77], v[14:15], v[20:21]
	v_pk_fma_f32 v[16:17], v[74:75], v[14:15], v[16:17]
	v_pk_fma_f32 v[14:15], v[72:73], v[14:15], v[30:31]
	v_pk_fma_f32 v[26:27], v[70:71], v[12:13], v[26:27]
	v_pk_fma_f32 v[24:25], v[68:69], v[12:13], v[24:25]
	v_pk_fma_f32 v[124:125], v[66:67], v[12:13], v[124:125]
	v_pk_fma_f32 v[126:127], v[66:67], v[10:11], v[126:127]
	v_pk_fma_f32 v[128:129], v[66:67], v[8:9], v[128:129]
	v_pk_fma_f32 v[130:131], v[66:67], v[6:7], v[130:131]
	s_waitcnt lgkmcnt(5)
	v_lshlrev_b32_e32 v136, 16, v48
	v_and_b32_e32 v137, 0xffff0000, v48
	v_pk_fma_f32 v[132:133], v[68:69], v[36:37], v[132:133]
	v_pk_fma_f32 v[4:5], v[88:89], v[12:13], v[4:5]
	v_pk_fma_f32 v[2:3], v[86:87], v[12:13], v[2:3]
	v_pk_fma_f32 v[0:1], v[84:85], v[12:13], v[0:1]
	v_pk_fma_f32 v[18:19], v[82:83], v[12:13], v[18:19]
	v_pk_fma_f32 v[22:23], v[80:81], v[12:13], v[22:23]
	v_pk_fma_f32 v[20:21], v[78:79], v[12:13], v[20:21]
	v_pk_fma_f32 v[16:17], v[76:77], v[12:13], v[16:17]
	v_pk_fma_f32 v[14:15], v[74:75], v[12:13], v[14:15]
	v_pk_fma_f32 v[12:13], v[72:73], v[12:13], v[28:29]
	v_pk_fma_f32 v[24:25], v[70:71], v[10:11], v[24:25]
	v_pk_fma_f32 v[124:125], v[68:69], v[10:11], v[124:125]
	v_pk_fma_f32 v[126:127], v[68:69], v[8:9], v[126:127]
	v_pk_fma_f32 v[128:129], v[68:69], v[6:7], v[128:129]
	v_pk_fma_f32 v[130:131], v[68:69], v[40:41], v[130:131]
	v_pk_fma_f32 v[132:133], v[70:71], v[136:137], v[132:133]
	s_waitcnt lgkmcnt(4)
	v_lshlrev_b32_e32 v134, 16, v207
	v_and_b32_e32 v135, 0xffff0000, v207
	v_pk_fma_f32 v[4:5], v[90:91], v[10:11], v[4:5]
	v_pk_fma_f32 v[2:3], v[88:89], v[10:11], v[2:3]
	v_pk_fma_f32 v[0:1], v[86:87], v[10:11], v[0:1]
	v_pk_fma_f32 v[18:19], v[84:85], v[10:11], v[18:19]
	v_pk_fma_f32 v[22:23], v[82:83], v[10:11], v[22:23]
	v_pk_fma_f32 v[20:21], v[80:81], v[10:11], v[20:21]
	v_pk_fma_f32 v[16:17], v[78:79], v[10:11], v[16:17]
	v_pk_fma_f32 v[14:15], v[76:77], v[10:11], v[14:15]
	v_pk_fma_f32 v[12:13], v[74:75], v[10:11], v[12:13]
	v_pk_fma_f32 v[10:11], v[72:73], v[10:11], v[26:27]
	v_pk_fma_f32 v[124:125], v[70:71], v[8:9], v[124:125]
	v_pk_fma_f32 v[126:127], v[70:71], v[6:7], v[126:127]
	v_pk_fma_f32 v[128:129], v[70:71], v[40:41], v[128:129]
	v_pk_fma_f32 v[130:131], v[70:71], v[36:37], v[130:131]
	s_waitcnt lgkmcnt(3)
	v_lshlrev_b32_e32 v138, 16, v208
	v_and_b32_e32 v139, 0xffff0000, v208
	v_pk_fma_f32 v[4:5], v[92:93], v[8:9], v[4:5]
	v_pk_fma_f32 v[2:3], v[90:91], v[8:9], v[2:3]
	v_pk_fma_f32 v[0:1], v[88:89], v[8:9], v[0:1]
	v_pk_fma_f32 v[18:19], v[86:87], v[8:9], v[18:19]
	v_pk_fma_f32 v[22:23], v[84:85], v[8:9], v[22:23]
	v_pk_fma_f32 v[20:21], v[82:83], v[8:9], v[20:21]
	v_pk_fma_f32 v[16:17], v[80:81], v[8:9], v[16:17]
	v_pk_fma_f32 v[14:15], v[78:79], v[8:9], v[14:15]
	v_pk_fma_f32 v[12:13], v[76:77], v[8:9], v[12:13]
	v_pk_fma_f32 v[10:11], v[74:75], v[8:9], v[10:11]
	v_pk_fma_f32 v[8:9], v[72:73], v[8:9], v[24:25]
	v_pk_fma_f32 v[32:33], v[72:73], v[134:135], v[132:133]
	s_waitcnt lgkmcnt(2)
	v_lshlrev_b32_e32 v140, 16, v209
	v_and_b32_e32 v141, 0xffff0000, v209
	v_pk_fma_f32 v[2:3], v[92:93], v[6:7], v[2:3]
	v_pk_fma_f32 v[0:1], v[90:91], v[6:7], v[0:1]
	v_pk_fma_f32 v[18:19], v[88:89], v[6:7], v[18:19]
	v_pk_fma_f32 v[22:23], v[86:87], v[6:7], v[22:23]
	v_pk_fma_f32 v[20:21], v[84:85], v[6:7], v[20:21]
	v_pk_fma_f32 v[16:17], v[82:83], v[6:7], v[16:17]
	v_pk_fma_f32 v[14:15], v[80:81], v[6:7], v[14:15]
	v_pk_fma_f32 v[12:13], v[78:79], v[6:7], v[12:13]
	v_pk_fma_f32 v[10:11], v[76:77], v[6:7], v[10:11]
	v_pk_fma_f32 v[8:9], v[74:75], v[6:7], v[8:9]
	v_pk_fma_f32 v[6:7], v[72:73], v[6:7], v[124:125]
	v_pk_fma_f32 v[24:25], v[72:73], v[40:41], v[126:127]
	v_pk_fma_f32 v[26:27], v[72:73], v[36:37], v[128:129]
	v_pk_fma_f32 v[28:29], v[72:73], v[136:137], v[130:131]
	v_pk_fma_f32 v[32:33], v[74:75], v[138:139], v[32:33]
	s_waitcnt lgkmcnt(1)
	v_lshlrev_b32_e32 v142, 16, v210
	v_and_b32_e32 v143, 0xffff0000, v210
	v_pk_fma_f32 v[6:7], v[74:75], v[40:41], v[6:7]
	v_pk_fma_f32 v[24:25], v[74:75], v[36:37], v[24:25]
	v_pk_fma_f32 v[26:27], v[74:75], v[136:137], v[26:27]
	v_pk_fma_f32 v[28:29], v[74:75], v[134:135], v[28:29]
	v_pk_fma_f32 v[32:33], v[76:77], v[140:141], v[32:33]
	s_waitcnt lgkmcnt(0)
	v_lshlrev_b32_e32 v144, 16, v211
	v_and_b32_e32 v145, 0xffff0000, v211
	v_pk_fma_f32 v[8:9], v[76:77], v[40:41], v[8:9]
	v_pk_fma_f32 v[6:7], v[76:77], v[36:37], v[6:7]
	v_pk_fma_f32 v[24:25], v[76:77], v[136:137], v[24:25]
	v_pk_fma_f32 v[26:27], v[76:77], v[134:135], v[26:27]
	v_pk_fma_f32 v[28:29], v[76:77], v[138:139], v[28:29]
	v_pk_fma_f32 v[32:33], v[78:79], v[142:143], v[32:33]
	ds_read_b32 v48, v173
	ds_read_b32 v149, v174
	ds_read_b32 v151, v175
	ds_read_b32 v153, v176
	ds_read_b32 v155, v177
	ds_read_b32 v207, v178
	s_waitcnt lgkmcnt(5)
; #define LAS __attribute__((address_space(3)))
; __global__ void __launch_bounds__(512, 2) fwd_kernel(Args a) {
;     ...
;             for (int j = 0; j < 31; ++j) {
; #pragma unroll
;                 for (int r = 0; r < 16; ++r) { const unsigned w = *(const LAS unsigned*)(lds + (r + j) * 2048 + tid * 4);
;                     acc[r][0] += wv[j][0] * bflo(w); acc[r][1] += wv[j][1] * bfhi(w); } }
;             __syncthreads();
; #pragma unroll
;             for (int r = 0; r < 16; ++r) { f32x2_t v = {acc[r][0], acc[r][1]}; *(LAS f32x2_t*)(lds + r * 4096 + tid * 8) = v; }
	v_lshlrev_b32_e32 v146, 16, v48
	v_and_b32_e32 v147, 0xffff0000, v48
	v_pk_fma_f32 v[10:11], v[78:79], v[40:41], v[10:11]
	v_pk_fma_f32 v[8:9], v[78:79], v[36:37], v[8:9]
	v_pk_fma_f32 v[6:7], v[78:79], v[136:137], v[6:7]
	v_pk_fma_f32 v[24:25], v[78:79], v[134:135], v[24:25]
	v_pk_fma_f32 v[26:27], v[78:79], v[138:139], v[26:27]
	v_pk_fma_f32 v[28:29], v[78:79], v[140:141], v[28:29]
	v_pk_fma_f32 v[32:33], v[80:81], v[144:145], v[32:33]
	s_waitcnt lgkmcnt(4)
	v_lshlrev_b32_e32 v148, 16, v149
	v_and_b32_e32 v149, 0xffff0000, v149
	v_pk_fma_f32 v[12:13], v[80:81], v[40:41], v[12:13]
	v_pk_fma_f32 v[10:11], v[80:81], v[36:37], v[10:11]
	v_pk_fma_f32 v[8:9], v[80:81], v[136:137], v[8:9]
	v_pk_fma_f32 v[6:7], v[80:81], v[134:135], v[6:7]
	v_pk_fma_f32 v[24:25], v[80:81], v[138:139], v[24:25]
	v_pk_fma_f32 v[26:27], v[80:81], v[140:141], v[26:27]
	v_pk_fma_f32 v[28:29], v[80:81], v[142:143], v[28:29]
	v_pk_fma_f32 v[32:33], v[82:83], v[146:147], v[32:33]
	s_waitcnt lgkmcnt(3)
	v_lshlrev_b32_e32 v150, 16, v151
	v_and_b32_e32 v151, 0xffff0000, v151
	v_pk_fma_f32 v[16:17], v[84:85], v[40:41], v[16:17]
	v_pk_fma_f32 v[14:15], v[82:83], v[40:41], v[14:15]
	v_pk_fma_f32 v[12:13], v[82:83], v[36:37], v[12:13]
	v_pk_fma_f32 v[10:11], v[82:83], v[136:137], v[10:11]
	v_pk_fma_f32 v[8:9], v[82:83], v[134:135], v[8:9]
	v_pk_fma_f32 v[6:7], v[82:83], v[138:139], v[6:7]
	v_pk_fma_f32 v[24:25], v[82:83], v[140:141], v[24:25]
	v_pk_fma_f32 v[26:27], v[82:83], v[142:143], v[26:27]
	v_pk_fma_f32 v[28:29], v[82:83], v[144:145], v[28:29]
	v_pk_fma_f32 v[32:33], v[84:85], v[148:149], v[32:33]
	s_waitcnt lgkmcnt(2)
	v_lshlrev_b32_e32 v152, 16, v153
	v_and_b32_e32 v153, 0xffff0000, v153
	v_pk_fma_f32 v[16:17], v[86:87], v[36:37], v[16:17]
	v_pk_fma_f32 v[14:15], v[84:85], v[36:37], v[14:15]
	v_pk_fma_f32 v[12:13], v[84:85], v[136:137], v[12:13]
	v_pk_fma_f32 v[10:11], v[84:85], v[134:135], v[10:11]
	v_pk_fma_f32 v[8:9], v[84:85], v[138:139], v[8:9]
	v_pk_fma_f32 v[6:7], v[84:85], v[140:141], v[6:7]
	v_pk_fma_f32 v[24:25], v[84:85], v[142:143], v[24:25]
	v_pk_fma_f32 v[26:27], v[84:85], v[144:145], v[26:27]
	v_pk_fma_f32 v[28:29], v[84:85], v[146:147], v[28:29]
	v_pk_fma_f32 v[32:33], v[86:87], v[150:151], v[32:33]
	s_waitcnt lgkmcnt(1)
	v_lshlrev_b32_e32 v154, 16, v155
	v_and_b32_e32 v155, 0xffff0000, v155
	v_pk_fma_f32 v[20:21], v[86:87], v[40:41], v[20:21]
	v_pk_fma_f32 v[16:17], v[88:89], v[136:137], v[16:17]
	v_pk_fma_f32 v[14:15], v[86:87], v[136:137], v[14:15]
	v_pk_fma_f32 v[12:13], v[86:87], v[134:135], v[12:13]
	v_pk_fma_f32 v[10:11], v[86:87], v[138:139], v[10:11]
	v_pk_fma_f32 v[8:9], v[86:87], v[140:141], v[8:9]
	v_pk_fma_f32 v[6:7], v[86:87], v[142:143], v[6:7]
	v_pk_fma_f32 v[24:25], v[86:87], v[144:145], v[24:25]
	v_pk_fma_f32 v[26:27], v[86:87], v[146:147], v[26:27]
	v_pk_fma_f32 v[28:29], v[86:87], v[148:149], v[28:29]
	v_pk_fma_f32 v[32:33], v[88:89], v[152:153], v[32:33]
	v_pk_fma_f32 v[22:23], v[88:89], v[40:41], v[22:23]
	v_pk_fma_f32 v[20:21], v[88:89], v[36:37], v[20:21]
	v_pk_fma_f32 v[16:17], v[90:91], v[134:135], v[16:17]
	v_pk_fma_f32 v[14:15], v[88:89], v[134:135], v[14:15]
	v_pk_fma_f32 v[12:13], v[88:89], v[138:139], v[12:13]
	v_pk_fma_f32 v[10:11], v[88:89], v[140:141], v[10:11]
	v_pk_fma_f32 v[8:9], v[88:89], v[142:143], v[8:9]
	v_pk_fma_f32 v[6:7], v[88:89], v[144:145], v[6:7]
	v_pk_fma_f32 v[24:25], v[88:89], v[146:147], v[24:25]
	v_pk_fma_f32 v[26:27], v[88:89], v[148:149], v[26:27]
	v_pk_fma_f32 v[28:29], v[88:89], v[150:151], v[28:29]
	s_waitcnt lgkmcnt(0)
	v_lshlrev_b32_e32 v30, 16, v207
	v_and_b32_e32 v31, 0xffff0000, v207
	v_pk_fma_f32 v[32:33], v[90:91], v[154:155], v[32:33]
	v_pk_fma_f32 v[18:19], v[90:91], v[40:41], v[18:19]
	v_pk_fma_f32 v[22:23], v[90:91], v[36:37], v[22:23]
	v_pk_fma_f32 v[20:21], v[90:91], v[136:137], v[20:21]
	v_pk_fma_f32 v[16:17], v[92:93], v[138:139], v[16:17]
	v_pk_fma_f32 v[14:15], v[90:91], v[138:139], v[14:15]
	v_pk_fma_f32 v[12:13], v[90:91], v[140:141], v[12:13]
	v_pk_fma_f32 v[10:11], v[90:91], v[142:143], v[10:11]
	v_pk_fma_f32 v[8:9], v[90:91], v[144:145], v[8:9]
	v_pk_fma_f32 v[6:7], v[90:91], v[146:147], v[6:7]
	v_pk_fma_f32 v[24:25], v[90:91], v[148:149], v[24:25]
	v_pk_fma_f32 v[26:27], v[90:91], v[150:151], v[26:27]
	v_pk_fma_f32 v[28:29], v[90:91], v[152:153], v[28:29]
	v_pk_fma_f32 v[30:31], v[92:93], v[30:31], v[32:33]
	v_add_u32_e32 v32, v157, v156
	v_pk_fma_f32 v[0:1], v[92:93], v[40:41], v[0:1]
	v_pk_fma_f32 v[18:19], v[92:93], v[36:37], v[18:19]
	v_pk_fma_f32 v[22:23], v[92:93], v[136:137], v[22:23]
	v_pk_fma_f32 v[20:21], v[92:93], v[134:135], v[20:21]
	v_pk_fma_f32 v[14:15], v[92:93], v[140:141], v[14:15]
	v_pk_fma_f32 v[12:13], v[92:93], v[142:143], v[12:13]
	v_pk_fma_f32 v[10:11], v[92:93], v[144:145], v[10:11]
	v_pk_fma_f32 v[8:9], v[92:93], v[146:147], v[8:9]
	v_pk_fma_f32 v[6:7], v[92:93], v[148:149], v[6:7]
	v_pk_fma_f32 v[24:25], v[92:93], v[150:151], v[24:25]
	v_pk_fma_f32 v[26:27], v[92:93], v[152:153], v[26:27]
	v_pk_fma_f32 v[28:29], v[92:93], v[154:155], v[28:29]
	s_barrier
	ds_write2st64_b64 v32, v[4:5], v[2:3] offset1:8
	ds_write2st64_b64 v32, v[0:1], v[18:19] offset0:16 offset1:24
	ds_write2st64_b64 v32, v[22:23], v[20:21] offset0:32 offset1:40
	ds_write2st64_b64 v32, v[16:17], v[14:15] offset0:48 offset1:56
	ds_write2st64_b64 v32, v[12:13], v[10:11] offset0:64 offset1:72
	ds_write2st64_b64 v32, v[8:9], v[6:7] offset0:80 offset1:88
	ds_write2st64_b64 v32, v[24:25], v[26:27] offset0:96 offset1:104
	ds_write2st64_b64 v32, v[28:29], v[30:31] offset0:112 offset1:120
	v_add_u32_e32 v16, s12, v158
	v_cmp_gt_i32_e32 vcc, s15, v16
	v_mbcnt_hi_u32_b32 v18, -1, v182
	s_waitcnt lgkmcnt(0)
	s_barrier
; #define LAS __attribute__((address_space(3)))
; __device__ __forceinline__ unsigned pk2(float lo, float hi) { f32x2_t v = {lo, hi}; bf16x2_t b = __builtin_convertvector(v, bf16x2_t); return __builtin_bit_cast(unsigned, b); }
; __device__ __forceinline__ float sigmoidf_(float x) { return __builtin_amdgcn_rcpf(1.0f + __expf(-x)); }
; __global__ void __launch_bounds__(512, 2) fwd_kernel(Args a) {
;     ...
;             for (int rr = 0; rr < 2; ++rr) { const int r = wave * 2 + rr, t = t0 + r;
;                 if (t < LSEQ) {
;                     f32x4 v[4]; float s = 0.f;
; #pragma unroll
;                     for (int j = 0; j < 4; ++j) { v[j] = *(const LAS f32x4*)(lds + r * 4096 + (lane + 64 * j) * 16); s += (v[j].x + v[j].y) + (v[j].z + v[j].w); }
;                     const float mu = wave_sum(s) * (1.0f / DM); float s2 = 0.f;
; #pragma unroll
;                     for (int j = 0; j < 4; ++j) { v[j] = v[j] - mu; s2 += (v[j].x * v[j].x + v[j].y * v[j].y) + (v[j].z * v[j].z + v[j].w * v[j].w); }
;                     const float rstd = 1.0f / sqrtf(wave_sum(s2) * (1.0f / DM) + 1e-5f);
; #pragma unroll
;                     for (int j = 0; j < 4; ++j) { const f32x4 gv = *((const f32x4*)a.c_lng + lane + 64 * j), bv = *((const f32x4*)a.c_lnb + lane + 64 * j);
;                         f32x4 y = v[j] * rstd * gv + bv; y.x *= sigmoidf_(y.x); y.y *= sigmoidf_(y.y); y.z *= sigmoidf_(y.z); y.w *= sigmoidf_(y.w);
;                         u32x2 o; o.x = pk2(y.x, y.y); o.y = pk2(y.z, y.w); *((u32x2*)(Z + (rb + t) * DM) + lane + 64 * j) = o; }
	s_and_saveexec_b64 s[12:13], vcc
	s_cbranch_execz .LBB0_1195
	v_add_u32_e32 v17, v159, v165
	ds_read_b128 v[12:15], v17
	ds_read_b128 v[8:11], v17 offset:1024
	ds_read_b128 v[4:7], v17 offset:2048
	v_and_b32_e32 v19, 64, v18
	v_add_u32_e32 v19, 64, v19
	s_waitcnt lgkmcnt(2)
	v_mov_b32_e32 v0, v13
	v_mov_b32_e32 v1, v14
	v_mov_b32_e32 v2, v12
	v_mov_b32_e32 v3, v15
	v_pk_add_f32 v[0:1], v[0:1], v[2:3]
	s_waitcnt lgkmcnt(1)
	v_mov_b32_e32 v22, v9
	v_add_f32_e32 v0, v0, v1
	v_add_f32_e32 v20, 0, v0
	ds_read_b128 v[0:3], v17 offset:3072
	v_mov_b32_e32 v23, v10
	v_mov_b32_e32 v24, v8
	v_mov_b32_e32 v25, v11
	v_pk_add_f32 v[22:23], v[22:23], v[24:25]
	s_waitcnt lgkmcnt(1)
	v_add_f32_e32 v24, v4, v5
	v_pk_add_f32 v[22:23], v[22:23], v[22:23] op_sel:[0,1] op_sel_hi:[1,0]
	v_add_f32_e32 v26, v6, v7
	s_waitcnt lgkmcnt(0)
	v_mov_b32_e32 v21, v0
	v_mov_b32_e32 v23, v1
	v_mov_b32_e32 v25, v2
	v_mov_b32_e32 v27, v3
	v_pk_add_f32 v[20:21], v[20:21], v[22:23]
	v_pk_add_f32 v[22:23], v[24:25], v[26:27]
	s_nop 0
	v_pk_add_f32 v[20:21], v[20:21], v[22:23]
	s_nop 0
	v_add_f32_e32 v17, v20, v21
	s_nop 1
	v_add_f32_dpp v17, v17, v17 quad_perm:[1,0,3,2] row_mask:0xf bank_mask:0xf
	s_nop 1
	v_add_f32_dpp v17, v17, v17 quad_perm:[2,3,0,1] row_mask:0xf bank_mask:0xf
	s_nop 1
	v_add_f32_dpp v17, v17, v17 row_half_mirror row_mask:0xf bank_mask:0xf
	s_nop 1
	v_add_f32_dpp v17, v17, v17 row_mirror row_mask:0xf bank_mask:0xf
	v_xor_b32_e32 v20, 16, v18
	v_cmp_lt_i32_e32 vcc, v20, v19
	s_nop 1
	v_cndmask_b32_e32 v20, v18, v20, vcc
	v_lshlrev_b32_e32 v36, 2, v20
	ds_bpermute_b32 v20, v36, v17
	s_waitcnt lgkmcnt(0)
	v_add_f32_e32 v17, v17, v20
	v_mov_b32_e32 v20, v17
	s_nop 1
	v_permlane32_swap_b32_e32 v20, v17
	v_add_f32_e32 v17, v17, v20
	v_fmamk_f32 v13, v17, 0xba800000, v13
	v_fmamk_f32 v12, v17, 0xba800000, v12
	v_fmamk_f32 v15, v17, 0xba800000, v15
	v_fmac_f32_e32 v14, 0xba800000, v17
	v_pk_mul_f32 v[20:21], v[14:15], v[14:15]
	v_pk_mul_f32 v[22:23], v[12:13], v[12:13]
	v_fmamk_f32 v9, v17, 0xba800000, v9
	v_pk_mov_b32 v[24:25], v[22:23], v[20:21] op_sel:[1,0]
	v_mov_b32_e32 v23, v21
	v_fmamk_f32 v8, v17, 0xba800000, v8
	v_fmamk_f32 v11, v17, 0xba800000, v11
	v_fmac_f32_e32 v10, 0xba800000, v17
	v_pk_add_f32 v[20:21], v[24:25], v[22:23]
	v_pk_mul_f32 v[22:23], v[10:11], v[10:11]
	v_pk_mul_f32 v[24:25], v[8:9], v[8:9]
	v_fmamk_f32 v1, v17, 0xba800000, v1
	v_pk_mov_b32 v[26:27], v[24:25], v[22:23] op_sel:[1,0]
	v_mov_b32_e32 v25, v23
	v_pk_add_f32 v[22:23], v[26:27], v[24:25]
	v_fmac_f32_e32 v0, 0xba800000, v17
	v_fmamk_f32 v5, v17, 0xba800000, v5
	v_fmamk_f32 v4, v17, 0xba800000, v4
	v_fmamk_f32 v7, v17, 0xba800000, v7
	v_fmac_f32_e32 v6, 0xba800000, v17
	v_fmamk_f32 v3, v17, 0xba800000, v3
	v_fmamk_f32 v2, v17, 0xba800000, v2
	v_mul_f32_e32 v17, v0, v0
	v_mul_f32_e32 v24, v1, v1
	v_pk_add_f32 v[20:21], v[20:21], v[20:21] op_sel:[0,1] op_sel_hi:[1,0]
	v_pk_add_f32 v[22:23], v[22:23], v[22:23] op_sel:[0,1] op_sel_hi:[1,0]
	v_mov_b32_e32 v21, v17
	v_mov_b32_e32 v23, v24
	v_pk_add_f32 v[28:29], v[20:21], v[22:23]
	v_mul_f32_e32 v20, v5, v5
	v_mul_f32_e32 v22, v7, v7
	v_mul_f32_e32 v25, v2, v2
	v_mul_f32_e32 v26, v3, v3
	v_pk_fma_f32 v[20:21], v[4:5], v[4:5], v[20:21] op_sel_hi:[1,1,0]
	v_pk_fma_f32 v[22:23], v[6:7], v[6:7], v[22:23] op_sel_hi:[1,1,0]
	v_mov_b32_e32 v21, v25
	v_mov_b32_e32 v23, v26
	v_pk_add_f32 v[30:31], v[20:21], v[22:23]
	v_pk_add_f32 v[28:29], v[28:29], v[30:31]
	s_nop 0
	v_add_f32_e32 v17, v28, v29
	s_nop 1
	v_add_f32_dpp v17, v17, v17 quad_perm:[1,0,3,2] row_mask:0xf bank_mask:0xf
	s_nop 1
	v_add_f32_dpp v17, v17, v17 quad_perm:[2,3,0,1] row_mask:0xf bank_mask:0xf
	s_nop 1
	v_add_f32_dpp v17, v17, v17 row_half_mirror row_mask:0xf bank_mask:0xf
	s_nop 1
	v_add_f32_dpp v17, v17, v17 row_mirror row_mask:0xf bank_mask:0xf
	ds_bpermute_b32 v28, v36, v17
	s_waitcnt lgkmcnt(0)
	v_add_f32_e32 v17, v17, v28
	v_mov_b32_e32 v19, v17
	s_nop 1
	v_permlane32_swap_b32_e32 v19, v17
	v_add_f32_e32 v17, v17, v19
	v_fmamk_f32 v17, v17, 0x3a800000, v204
	v_mul_f32_e32 v19, 0x4f800000, v17
	v_cmp_gt_f32_e32 vcc, s16, v17
	s_nop 1
	v_cndmask_b32_e32 v17, v17, v19, vcc
	v_sqrt_f32_e32 v19, v17
	s_nop 0
	v_add_u32_e32 v28, -1, v19
	v_fma_f32 v29, -v28, v19, v17
	v_cmp_ge_f32_e64 s[0:1], 0, v29
	v_add_u32_e32 v29, 1, v19
	s_nop 0
	v_cndmask_b32_e64 v28, v19, v28, s[0:1]
	v_fma_f32 v19, -v29, v19, v17
	v_cmp_lt_f32_e64 s[0:1], 0, v19
	s_nop 1
	v_cndmask_b32_e64 v19, v28, v29, s[0:1]
	v_mul_f32_e32 v28, 0x37800000, v19
	v_cndmask_b32_e32 v19, v19, v28, vcc
	v_cmp_class_f32_e32 vcc, v17, v205
	s_nop 1
	v_cndmask_b32_e32 v17, v19, v17, vcc
	v_div_scale_f32 v19, s[0:1], v17, v17, 1.0
	v_rcp_f32_e32 v28, v19
	s_nop 0
	v_fma_f32 v29, -v19, v28, 1.0
	v_fmac_f32_e32 v28, v29, v28
	v_div_scale_f32 v29, vcc, 1.0, v17, 1.0
	v_mul_f32_e32 v30, v29, v28
	v_fma_f32 v31, -v19, v30, v29
	v_fmac_f32_e32 v30, v31, v28
	v_fma_f32 v19, -v19, v30, v29
	v_div_fmas_f32 v19, v19, v28, v30
	v_div_fixup_f32 v28, v19, v17, 1.0
	v_pk_mul_f32 v[12:13], v[28:29], v[12:13] op_sel_hi:[0,1]
	v_ashrrev_i32_e32 v17, 31, v16
	v_pk_fma_f32 v[12:13], v[12:13], v[212:213], v[228:229]
	v_lshl_add_u64 v[30:31], s[10:11], 0, v[16:17]
	v_mul_f32_e32 v17, 0xbfb8aa3b, v12
	v_exp_f32_e32 v17, v17
	v_mul_f32_e32 v19, 0xbfb8aa3b, v13
	v_exp_f32_e32 v19, v19
	v_pk_mul_f32 v[14:15], v[28:29], v[14:15] op_sel_hi:[0,1]
	v_pk_fma_f32 v[14:15], v[14:15], v[214:215], v[230:231]
	v_add_f32_e32 v17, 1.0, v17
	v_rcp_f32_e32 v20, v17
	v_add_f32_e32 v17, 1.0, v19
	v_mul_f32_e32 v19, 0xbfb8aa3b, v14
	v_exp_f32_e32 v19, v19
	v_mul_f32_e32 v21, 0xbfb8aa3b, v15
	v_exp_f32_e32 v23, v21
	v_rcp_f32_e32 v21, v17
	v_add_f32_e32 v17, 1.0, v19
; #define LAS __attribute__((address_space(3)))
; __device__ __forceinline__ unsigned pk2(float lo, float hi) { f32x2_t v = {lo, hi}; bf16x2_t b = __builtin_convertvector(v, bf16x2_t); return __builtin_bit_cast(unsigned, b); }
; __device__ __forceinline__ float sigmoidf_(float x) { return __builtin_amdgcn_rcpf(1.0f + __expf(-x)); }
; __global__ void __launch_bounds__(512, 2) fwd_kernel(Args a) {
;     ...
;             for (int rr = 0; rr < 2; ++rr) { const int r = wave * 2 + rr, t = t0 + r;
;                 if (t < LSEQ) {
;                     f32x4 v[4]; float s = 0.f;
; #pragma unroll
;                     for (int j = 0; j < 4; ++j) { v[j] = *(const LAS f32x4*)(lds + r * 4096 + (lane + 64 * j) * 16); s += (v[j].x + v[j].y) + (v[j].z + v[j].w); }
;                     const float mu = wave_sum(s) * (1.0f / DM); float s2 = 0.f;
; #pragma unroll
;                     for (int j = 0; j < 4; ++j) { v[j] = v[j] - mu; s2 += (v[j].x * v[j].x + v[j].y * v[j].y) + (v[j].z * v[j].z + v[j].w * v[j].w); }
;                     const float rstd = 1.0f / sqrtf(wave_sum(s2) * (1.0f / DM) + 1e-5f);
; #pragma unroll
;                     for (int j = 0; j < 4; ++j) { const f32x4 gv = *((const f32x4*)a.c_lng + lane + 64 * j), bv = *((const f32x4*)a.c_lnb + lane + 64 * j);
;                         f32x4 y = v[j] * rstd * gv + bv; y.x *= sigmoidf_(y.x); y.y *= sigmoidf_(y.y); y.z *= sigmoidf_(y.z); y.w *= sigmoidf_(y.w);
;                         u32x2 o; o.x = pk2(y.x, y.y); o.y = pk2(y.z, y.w); *((u32x2*)(Z + (rb + t) * DM) + lane + 64 * j) = o; }
	v_rcp_f32_e32 v22, v17
	v_add_f32_e32 v17, 1.0, v23
	v_rcp_f32_e32 v23, v17
	v_lshlrev_b64 v[24:25], 11, v[30:31]
	v_pk_mul_f32 v[12:13], v[12:13], v[20:21]
	v_lshl_add_u64 v[24:25], v[120:121], 0, v[24:25]
	v_pk_mul_f32 v[14:15], v[14:15], v[22:23]
	v_cvt_pk_bf16_f32 v12, v12, v13
	v_cvt_pk_bf16_f32 v13, v14, v15
	global_store_dwordx2 v[24:25], v[12:13], off
	s_nop 0
	v_pk_mul_f32 v[8:9], v[28:29], v[8:9] op_sel_hi:[0,1]
	v_pk_mul_f32 v[10:11], v[28:29], v[10:11] op_sel_hi:[0,1]
	v_pk_mul_f32 v[4:5], v[28:29], v[4:5] op_sel_hi:[0,1]
	v_pk_mul_f32 v[6:7], v[28:29], v[6:7] op_sel_hi:[0,1]
	v_pk_mul_f32 v[0:1], v[28:29], v[0:1] op_sel_hi:[0,1]
	v_pk_mul_f32 v[2:3], v[28:29], v[2:3] op_sel_hi:[0,1]
	v_pk_fma_f32 v[10:11], v[10:11], v[218:219], v[234:235]
	v_pk_fma_f32 v[8:9], v[8:9], v[216:217], v[232:233]
	v_mul_f32_e32 v14, 0xbfb8aa3b, v10
	v_mul_f32_e32 v12, 0xbfb8aa3b, v8
	v_mul_f32_e32 v13, 0xbfb8aa3b, v9
	v_mul_f32_e32 v15, 0xbfb8aa3b, v11
	v_exp_f32_e32 v12, v12
	v_exp_f32_e32 v13, v13
	v_exp_f32_e32 v14, v14
	v_exp_f32_e32 v15, v15
	v_add_f32_e32 v12, 1.0, v12
	v_add_f32_e32 v13, 1.0, v13
	v_add_f32_e32 v14, 1.0, v14
	v_add_f32_e32 v15, 1.0, v15
	v_rcp_f32_e32 v12, v12
	v_rcp_f32_e32 v13, v13
	v_rcp_f32_e32 v14, v14
	v_rcp_f32_e32 v15, v15
	v_pk_mul_f32 v[8:9], v[8:9], v[12:13]
	s_nop 0
	v_cvt_pk_bf16_f32 v8, v8, v9
	v_pk_mul_f32 v[10:11], v[10:11], v[14:15]
	s_nop 0
	v_cvt_pk_bf16_f32 v9, v10, v11
	global_store_dwordx2 v[24:25], v[8:9], off offset:512
	s_nop 0
	v_pk_fma_f32 v[6:7], v[6:7], v[222:223], v[238:239]
	v_pk_fma_f32 v[4:5], v[4:5], v[220:221], v[236:237]
	v_mul_f32_e32 v10, 0xbfb8aa3b, v6
	v_mul_f32_e32 v8, 0xbfb8aa3b, v4
	v_mul_f32_e32 v9, 0xbfb8aa3b, v5
	v_mul_f32_e32 v11, 0xbfb8aa3b, v7
	v_exp_f32_e32 v8, v8
	v_exp_f32_e32 v9, v9
	v_exp_f32_e32 v10, v10
	v_exp_f32_e32 v11, v11
	v_add_f32_e32 v8, 1.0, v8
	v_add_f32_e32 v9, 1.0, v9
	v_add_f32_e32 v10, 1.0, v10
	v_add_f32_e32 v11, 1.0, v11
	v_rcp_f32_e32 v8, v8
	v_rcp_f32_e32 v9, v9
	v_rcp_f32_e32 v10, v10
	v_rcp_f32_e32 v11, v11
	v_pk_mul_f32 v[4:5], v[4:5], v[8:9]
	s_nop 0
	v_cvt_pk_bf16_f32 v4, v4, v5
	v_pk_mul_f32 v[6:7], v[6:7], v[10:11]
	s_nop 0
	v_cvt_pk_bf16_f32 v5, v6, v7
	global_store_dwordx2 v[24:25], v[4:5], off offset:1024
	s_nop 0
	v_pk_fma_f32 v[2:3], v[2:3], v[226:227], v[242:243]
	v_pk_fma_f32 v[0:1], v[0:1], v[224:225], v[240:241]
	v_mul_f32_e32 v6, 0xbfb8aa3b, v2
	v_mul_f32_e32 v4, 0xbfb8aa3b, v0
	v_mul_f32_e32 v5, 0xbfb8aa3b, v1
	v_mul_f32_e32 v7, 0xbfb8aa3b, v3
	v_exp_f32_e32 v4, v4
	v_exp_f32_e32 v5, v5
	v_exp_f32_e32 v6, v6
	v_exp_f32_e32 v7, v7
	v_add_f32_e32 v4, 1.0, v4
	v_add_f32_e32 v5, 1.0, v5
	v_add_f32_e32 v6, 1.0, v6
	v_add_f32_e32 v7, 1.0, v7
	v_rcp_f32_e32 v4, v4
	v_rcp_f32_e32 v5, v5
	v_rcp_f32_e32 v6, v6
	v_rcp_f32_e32 v7, v7
	v_pk_mul_f32 v[0:1], v[0:1], v[4:5]
	s_nop 0
	v_cvt_pk_bf16_f32 v0, v0, v1
	v_pk_mul_f32 v[2:3], v[2:3], v[6:7]
	s_nop 0
	v_cvt_pk_bf16_f32 v1, v2, v3
	global_store_dwordx2 v[24:25], v[0:1], off offset:1536
.LBB0_1195:
	s_or_b64 exec, exec, s[12:13]
	v_add_u32_e32 v16, 1, v16
	v_cmp_gt_i32_e32 vcc, s15, v16
	s_and_saveexec_b64 s[12:13], vcc
	s_cbranch_execz .LBB0_1164
	ds_read_b128 v[12:15], v206
	ds_read_b128 v[8:11], v206 offset:1024
	ds_read_b128 v[4:7], v206 offset:2048
	v_and_b32_e32 v19, 64, v18
	v_add_u32_e32 v19, 64, v19
	s_waitcnt lgkmcnt(2)
	v_mov_b32_e32 v0, v13
	v_mov_b32_e32 v1, v14
	v_mov_b32_e32 v2, v12
	v_mov_b32_e32 v3, v15
	v_pk_add_f32 v[0:1], v[0:1], v[2:3]
	s_waitcnt lgkmcnt(1)
	v_mov_b32_e32 v22, v9
	v_add_f32_e32 v0, v0, v1
	v_add_f32_e32 v20, 0, v0
	ds_read_b128 v[0:3], v206 offset:3072
	v_mov_b32_e32 v23, v10
	v_mov_b32_e32 v24, v8
	v_mov_b32_e32 v25, v11
	v_pk_add_f32 v[22:23], v[22:23], v[24:25]
	s_waitcnt lgkmcnt(1)
	v_add_f32_e32 v24, v4, v5
	v_pk_add_f32 v[22:23], v[22:23], v[22:23] op_sel:[0,1] op_sel_hi:[1,0]
	v_add_f32_e32 v26, v6, v7
	s_waitcnt lgkmcnt(0)
	v_mov_b32_e32 v21, v0
	v_mov_b32_e32 v23, v1
	v_mov_b32_e32 v25, v2
	v_mov_b32_e32 v27, v3
	v_pk_add_f32 v[20:21], v[20:21], v[22:23]
	v_pk_add_f32 v[22:23], v[24:25], v[26:27]
	s_nop 0
	v_pk_add_f32 v[20:21], v[20:21], v[22:23]
	s_nop 0
	v_add_f32_e32 v17, v20, v21
	s_nop 1
	v_add_f32_dpp v17, v17, v17 quad_perm:[1,0,3,2] row_mask:0xf bank_mask:0xf
	s_nop 1
	v_add_f32_dpp v17, v17, v17 quad_perm:[2,3,0,1] row_mask:0xf bank_mask:0xf
	s_nop 1
	v_add_f32_dpp v17, v17, v17 row_half_mirror row_mask:0xf bank_mask:0xf
	s_nop 1
	v_add_f32_dpp v17, v17, v17 row_mirror row_mask:0xf bank_mask:0xf
	v_xor_b32_e32 v20, 16, v18
	v_cmp_lt_i32_e32 vcc, v20, v19
	s_nop 1
	v_cndmask_b32_e32 v20, v18, v20, vcc
	v_lshlrev_b32_e32 v34, 2, v20
	ds_bpermute_b32 v20, v34, v17
	s_waitcnt lgkmcnt(0)
; #define LAS __attribute__((address_space(3)))
; __device__ __forceinline__ unsigned pk2(float lo, float hi) { f32x2_t v = {lo, hi}; bf16x2_t b = __builtin_convertvector(v, bf16x2_t); return __builtin_bit_cast(unsigned, b); }
; __device__ __forceinline__ float sigmoidf_(float x) { return __builtin_amdgcn_rcpf(1.0f + __expf(-x)); }
; __global__ void __launch_bounds__(512, 2) fwd_kernel(Args a) {
;     ...
;             for (int rr = 0; rr < 2; ++rr) { const int r = wave * 2 + rr, t = t0 + r;
;                 if (t < LSEQ) {
;                     f32x4 v[4]; float s = 0.f;
; #pragma unroll
;                     for (int j = 0; j < 4; ++j) { v[j] = *(const LAS f32x4*)(lds + r * 4096 + (lane + 64 * j) * 16); s += (v[j].x + v[j].y) + (v[j].z + v[j].w); }
;                     const float mu = wave_sum(s) * (1.0f / DM); float s2 = 0.f;
; #pragma unroll
;                     for (int j = 0; j < 4; ++j) { v[j] = v[j] - mu; s2 += (v[j].x * v[j].x + v[j].y * v[j].y) + (v[j].z * v[j].z + v[j].w * v[j].w); }
;                     const float rstd = 1.0f / sqrtf(wave_sum(s2) * (1.0f / DM) + 1e-5f);
; #pragma unroll
;                     for (int j = 0; j < 4; ++j) { const f32x4 gv = *((const f32x4*)a.c_lng + lane + 64 * j), bv = *((const f32x4*)a.c_lnb + lane + 64 * j);
;                         f32x4 y = v[j] * rstd * gv + bv; y.x *= sigmoidf_(y.x); y.y *= sigmoidf_(y.y); y.z *= sigmoidf_(y.z); y.w *= sigmoidf_(y.w);
;                         u32x2 o; o.x = pk2(y.x, y.y); o.y = pk2(y.z, y.w); *((u32x2*)(Z + (rb + t) * DM) + lane + 64 * j) = o; }
;                 } }
;             __syncthreads();
	v_add_f32_e32 v17, v17, v20
	v_mov_b32_e32 v18, v17
	s_nop 1
	v_permlane32_swap_b32_e32 v18, v17
	v_add_f32_e32 v17, v17, v18
	v_fmamk_f32 v13, v17, 0xba800000, v13
	v_fmamk_f32 v12, v17, 0xba800000, v12
	v_fmamk_f32 v15, v17, 0xba800000, v15
	v_fmac_f32_e32 v14, 0xba800000, v17
	v_pk_mul_f32 v[18:19], v[14:15], v[14:15]
	v_pk_mul_f32 v[20:21], v[12:13], v[12:13]
	v_fmamk_f32 v9, v17, 0xba800000, v9
	v_pk_mov_b32 v[22:23], v[20:21], v[18:19] op_sel:[1,0]
	v_mov_b32_e32 v21, v19
	v_fmamk_f32 v8, v17, 0xba800000, v8
	v_fmamk_f32 v11, v17, 0xba800000, v11
	v_fmac_f32_e32 v10, 0xba800000, v17
	v_pk_add_f32 v[18:19], v[22:23], v[20:21]
	v_pk_mul_f32 v[20:21], v[10:11], v[10:11]
	v_pk_mul_f32 v[22:23], v[8:9], v[8:9]
	v_fmamk_f32 v1, v17, 0xba800000, v1
	v_pk_mov_b32 v[24:25], v[22:23], v[20:21] op_sel:[1,0]
	v_mov_b32_e32 v23, v21
	v_pk_add_f32 v[20:21], v[24:25], v[22:23]
	v_fmac_f32_e32 v0, 0xba800000, v17
	v_fmamk_f32 v5, v17, 0xba800000, v5
	v_fmamk_f32 v4, v17, 0xba800000, v4
	v_fmamk_f32 v7, v17, 0xba800000, v7
	v_fmac_f32_e32 v6, 0xba800000, v17
	v_fmamk_f32 v3, v17, 0xba800000, v3
	v_fmamk_f32 v2, v17, 0xba800000, v2
	v_mul_f32_e32 v17, v0, v0
	v_mul_f32_e32 v22, v1, v1
	v_pk_add_f32 v[18:19], v[18:19], v[18:19] op_sel:[0,1] op_sel_hi:[1,0]
	v_pk_add_f32 v[20:21], v[20:21], v[20:21] op_sel:[0,1] op_sel_hi:[1,0]
	v_mov_b32_e32 v19, v17
	v_mov_b32_e32 v21, v22
	v_pk_add_f32 v[26:27], v[18:19], v[20:21]
	v_mul_f32_e32 v18, v5, v5
	v_mul_f32_e32 v20, v7, v7
	v_mul_f32_e32 v23, v2, v2
	v_mul_f32_e32 v24, v3, v3
	v_pk_fma_f32 v[18:19], v[4:5], v[4:5], v[18:19] op_sel_hi:[1,1,0]
	v_pk_fma_f32 v[20:21], v[6:7], v[6:7], v[20:21] op_sel_hi:[1,1,0]
	v_mov_b32_e32 v19, v23
	v_mov_b32_e32 v21, v24
	v_pk_add_f32 v[28:29], v[18:19], v[20:21]
	v_pk_add_f32 v[26:27], v[26:27], v[28:29]
	s_nop 0
	v_add_f32_e32 v17, v26, v27
	s_nop 1
	v_add_f32_dpp v17, v17, v17 quad_perm:[1,0,3,2] row_mask:0xf bank_mask:0xf
	s_nop 1
	v_add_f32_dpp v17, v17, v17 quad_perm:[2,3,0,1] row_mask:0xf bank_mask:0xf
	s_nop 1
	v_add_f32_dpp v17, v17, v17 row_half_mirror row_mask:0xf bank_mask:0xf
	s_nop 1
	v_add_f32_dpp v17, v17, v17 row_mirror row_mask:0xf bank_mask:0xf
	ds_bpermute_b32 v26, v34, v17
	s_waitcnt lgkmcnt(0)
	v_add_f32_e32 v17, v17, v26
	v_mov_b32_e32 v26, v17
	s_nop 1
	v_permlane32_swap_b32_e32 v26, v17
	v_add_f32_e32 v17, v17, v26
	v_fmamk_f32 v17, v17, 0x3a800000, v204
	v_mul_f32_e32 v26, 0x4f800000, v17
	v_cmp_gt_f32_e32 vcc, s16, v17
	s_nop 1
	v_cndmask_b32_e32 v17, v17, v26, vcc
	v_sqrt_f32_e32 v26, v17
	s_nop 0
	v_add_u32_e32 v27, -1, v26
	v_fma_f32 v28, -v27, v26, v17
	v_cmp_ge_f32_e64 s[0:1], 0, v28
	v_add_u32_e32 v28, 1, v26
	s_nop 0
	v_cndmask_b32_e64 v27, v26, v27, s[0:1]
	v_fma_f32 v26, -v28, v26, v17
	v_cmp_lt_f32_e64 s[0:1], 0, v26
	s_nop 1
	v_cndmask_b32_e64 v26, v27, v28, s[0:1]
	v_mul_f32_e32 v27, 0x37800000, v26
	v_cndmask_b32_e32 v26, v26, v27, vcc
	v_cmp_class_f32_e32 vcc, v17, v205
	s_nop 1
	v_cndmask_b32_e32 v17, v26, v17, vcc
	v_div_scale_f32 v26, s[0:1], v17, v17, 1.0
	v_rcp_f32_e32 v27, v26
	s_nop 0
	v_fma_f32 v28, -v26, v27, 1.0
	v_fmac_f32_e32 v27, v28, v27
	v_div_scale_f32 v28, vcc, 1.0, v17, 1.0
	v_mul_f32_e32 v29, v28, v27
	v_fma_f32 v30, -v26, v29, v28
	v_fmac_f32_e32 v29, v30, v27
	v_fma_f32 v26, -v26, v29, v28
	v_div_fmas_f32 v26, v26, v27, v29
	v_div_fixup_f32 v26, v26, v17, 1.0
	v_pk_mul_f32 v[12:13], v[26:27], v[12:13] op_sel_hi:[0,1]
	v_pk_mul_f32 v[14:15], v[26:27], v[14:15] op_sel_hi:[0,1]
	v_pk_fma_f32 v[12:13], v[12:13], v[212:213], v[228:229]
	v_pk_fma_f32 v[14:15], v[14:15], v[214:215], v[230:231]
	v_mul_f32_e32 v18, 0xbfb8aa3b, v12
	v_mul_f32_e32 v19, 0xbfb8aa3b, v13
	v_mul_f32_e32 v20, 0xbfb8aa3b, v14
	v_mul_f32_e32 v21, 0xbfb8aa3b, v15
	v_exp_f32_e32 v18, v18
	v_exp_f32_e32 v19, v19
	v_exp_f32_e32 v20, v20
	v_exp_f32_e32 v21, v21
	v_add_f32_e32 v18, 1.0, v18
	v_add_f32_e32 v19, 1.0, v19
	v_add_f32_e32 v20, 1.0, v20
	v_add_f32_e32 v21, 1.0, v21
	v_rcp_f32_e32 v18, v18
	v_rcp_f32_e32 v19, v19
	v_rcp_f32_e32 v20, v20
	v_rcp_f32_e32 v21, v21
	v_ashrrev_i32_e32 v17, 31, v16
	v_lshl_add_u64 v[16:17], s[10:11], 0, v[16:17]
	v_lshlrev_b64 v[16:17], 11, v[16:17]
	v_pk_mul_f32 v[12:13], v[12:13], v[18:19]
	v_pk_mul_f32 v[14:15], v[14:15], v[20:21]
	v_lshl_add_u64 v[22:23], v[120:121], 0, v[16:17]
	v_cvt_pk_bf16_f32 v12, v12, v13
	v_cvt_pk_bf16_f32 v13, v14, v15
	global_store_dwordx2 v[22:23], v[12:13], off
	s_nop 0
	v_pk_mul_f32 v[8:9], v[26:27], v[8:9] op_sel_hi:[0,1]
	v_pk_mul_f32 v[10:11], v[26:27], v[10:11] op_sel_hi:[0,1]
	v_pk_mul_f32 v[4:5], v[26:27], v[4:5] op_sel_hi:[0,1]
	v_pk_mul_f32 v[6:7], v[26:27], v[6:7] op_sel_hi:[0,1]
	v_pk_mul_f32 v[0:1], v[26:27], v[0:1] op_sel_hi:[0,1]
	v_pk_mul_f32 v[2:3], v[26:27], v[2:3] op_sel_hi:[0,1]
	v_pk_fma_f32 v[10:11], v[10:11], v[218:219], v[234:235]
	v_pk_fma_f32 v[8:9], v[8:9], v[216:217], v[232:233]
	v_mul_f32_e32 v14, 0xbfb8aa3b, v10
	v_mul_f32_e32 v12, 0xbfb8aa3b, v8
	v_mul_f32_e32 v13, 0xbfb8aa3b, v9
	v_mul_f32_e32 v15, 0xbfb8aa3b, v11
	v_exp_f32_e32 v12, v12
	v_exp_f32_e32 v13, v13
	v_exp_f32_e32 v14, v14
	v_exp_f32_e32 v15, v15
	v_add_f32_e32 v12, 1.0, v12
	v_add_f32_e32 v13, 1.0, v13
	v_add_f32_e32 v14, 1.0, v14
	v_add_f32_e32 v15, 1.0, v15
	v_rcp_f32_e32 v12, v12
	v_rcp_f32_e32 v13, v13
	v_rcp_f32_e32 v14, v14
	v_rcp_f32_e32 v15, v15
	v_pk_mul_f32 v[8:9], v[8:9], v[12:13]
	s_nop 0
	v_cvt_pk_bf16_f32 v8, v8, v9
	v_pk_mul_f32 v[10:11], v[10:11], v[14:15]
	s_nop 0
	v_cvt_pk_bf16_f32 v9, v10, v11
	global_store_dwordx2 v[22:23], v[8:9], off offset:512
	s_nop 0
	v_pk_fma_f32 v[6:7], v[6:7], v[222:223], v[238:239]
	v_pk_fma_f32 v[4:5], v[4:5], v[220:221], v[236:237]
	v_mul_f32_e32 v10, 0xbfb8aa3b, v6
	v_mul_f32_e32 v8, 0xbfb8aa3b, v4
	v_mul_f32_e32 v9, 0xbfb8aa3b, v5
	v_mul_f32_e32 v11, 0xbfb8aa3b, v7
	v_exp_f32_e32 v8, v8
	v_exp_f32_e32 v9, v9
	v_exp_f32_e32 v10, v10
	v_exp_f32_e32 v11, v11
	v_add_f32_e32 v8, 1.0, v8
	v_add_f32_e32 v9, 1.0, v9
	v_add_f32_e32 v10, 1.0, v10
	v_add_f32_e32 v11, 1.0, v11
	v_rcp_f32_e32 v8, v8
	v_rcp_f32_e32 v9, v9
	v_rcp_f32_e32 v10, v10
	v_rcp_f32_e32 v11, v11
	v_pk_mul_f32 v[4:5], v[4:5], v[8:9]
	s_nop 0
	v_cvt_pk_bf16_f32 v4, v4, v5
	v_pk_mul_f32 v[6:7], v[6:7], v[10:11]
	s_nop 0
	v_cvt_pk_bf16_f32 v5, v6, v7
	global_store_dwordx2 v[22:23], v[4:5], off offset:1024
	s_nop 0
	v_pk_fma_f32 v[2:3], v[2:3], v[226:227], v[242:243]
	v_pk_fma_f32 v[0:1], v[0:1], v[224:225], v[240:241]
	v_mul_f32_e32 v6, 0xbfb8aa3b, v2
	v_mul_f32_e32 v4, 0xbfb8aa3b, v0
	v_mul_f32_e32 v5, 0xbfb8aa3b, v1
	v_mul_f32_e32 v7, 0xbfb8aa3b, v3
	v_exp_f32_e32 v4, v4
	v_exp_f32_e32 v5, v5
	v_exp_f32_e32 v6, v6
	v_exp_f32_e32 v7, v7
	v_add_f32_e32 v4, 1.0, v4
	v_add_f32_e32 v5, 1.0, v5
	v_add_f32_e32 v6, 1.0, v6
	v_add_f32_e32 v7, 1.0, v7
	v_rcp_f32_e32 v4, v4
	v_rcp_f32_e32 v5, v5
	v_rcp_f32_e32 v6, v6
	v_rcp_f32_e32 v7, v7
	v_pk_mul_f32 v[0:1], v[0:1], v[4:5]
	s_nop 0
	v_cvt_pk_bf16_f32 v0, v0, v1
	v_pk_mul_f32 v[2:3], v[2:3], v[6:7]
	s_nop 0
	v_cvt_pk_bf16_f32 v1, v2, v3
	global_store_dwordx2 v[22:23], v[0:1], off offset:1536
	s_branch .LBB0_1164
